# ACBD
# speedup vs baseline: 1.0237x; 1.0128x over previous
;     ...
;   const int ntn = Npad / 256, ntk = K / 64;
;   const int total = (it_end < 0) ? ntn * ntk : it_end;
;   if (bid < 0) { bid = blockIdx.x; nb = gridDim.x; }
;   const int tid = opaque_tid();
;   for (int it = it_begin + bid; it < total; it += nb) {
;     const int tn = it % ntn, tk = it / ntn;
;     const int k0 = tk * 64, n0 = tn * 256;
;     f32x4 v[8];
; #pragma unroll
;     for (int i = 0; i < 8; ++i) {
;       const int id = tid + i * 512;
;       const int r = id >> 6, c4 = (id & 63) * 4;
;       v[i] = (f32x4){0.f, 0.f, 0.f, 0.f};
;       if (n0 + c4 < N) v[i] = __builtin_nontemporal_load((const f32x4*)(src + (size_t)(k0 + r) * N + n0 + c4));
; __global__ void __launch_bounds__(NTHREADS) fwd_megakernel(Params p_unused) {
;     ...
;     {
;       CParamsPtr k = fresh_params();
;       transpose_convert_wide(k->w_out + (size_t)l * DM * DM, (bf16_t*)(k->ws + WS_WOUTT) + (size_t)l * DM * DM, DM, DM, DM);
;     }
.LBB0_27:
	s_mov_b64 s[44:45], s[0:1]
	v_mov_b32_e32 v2, v254
	s_and_b64 vcc, exec, s[6:7]
	s_cbranch_vccnz .LBB0_46
	s_cmp_eq_u32 s12, 1
	s_cbranch_scc1 .LBB0_46
	s_load_dwordx2 s[46:47], s[44:45], 0x68
	s_nop 0
	s_load_dwordx2 s[44:45], s[44:45], 0x48
	s_lshl_b64 s[48:49], s[12:13], 25
	v_lshlrev_b32_e32 v1, 2, v2
	v_and_b32_e32 v1, 0xfc, v1
	s_waitcnt lgkmcnt(0)
	s_add_u32 s46, s46, s48
	s_addc_u32 s47, s47, s49
	s_lshl_b64 s[48:49], s[12:13], 26
	s_add_u32 s44, s44, s48
	v_lshlrev_b32_e32 v4, 3, v2
	s_addc_u32 s45, s45, s49
	v_lshlrev_b32_e32 v34, 2, v1
	v_and_b32_e32 v4, 56, v4
	v_lshl_add_u64 v[36:37], s[44:45], 0, v[34:35]
	v_add_u32_e32 v3, 16, v34
	v_lshlrev_b32_e32 v34, 1, v4
	v_add_u32_e32 v8, 0x800, v2
	v_mad_u32_u24 v6, v4, s59, 16
	v_lshl_add_u64 v[4:5], s[46:47], 0, v[34:35]
	v_ashrrev_i32_e32 v47, 6, v8
	v_add_u32_e32 v8, 0xa00, v2
	v_lshl_add_u64 v[38:39], v[4:5], 0, s[42:43]
	v_ashrrev_i32_e32 v34, 3, v2
	v_ashrrev_i32_e32 v43, 6, v2
	v_add_u32_e32 v4, 0x200, v2
	v_add_u32_e32 v5, 0x400, v2
	v_add_u32_e32 v7, 0x600, v2
	v_ashrrev_i32_e32 v48, 6, v8
	v_add_u32_e32 v8, 0xc00, v2
	v_add_u32_e32 v2, 0xe00, v2
	v_ashrrev_i32_e32 v44, 6, v4
	v_ashrrev_i32_e32 v45, 6, v5
	v_ashrrev_i32_e32 v46, 6, v7
	v_ashrrev_i32_e32 v49, 6, v8
	v_ashrrev_i32_e32 v50, 6, v2
	v_mul_lo_u32 v2, v43, s59
	v_mul_lo_u32 v8, v44, s59
	v_mul_lo_u32 v9, v45, s59
	v_mul_lo_u32 v10, v46, s59
	v_mul_lo_u32 v11, v47, s59
	v_mul_lo_u32 v12, v48, s59
	v_mul_lo_u32 v13, v49, s59
	v_ashrrev_i32_e32 v51, 3, v4
	v_ashrrev_i32_e32 v53, 3, v5
	v_ashrrev_i32_e32 v55, 3, v7
	v_mul_lo_u32 v4, v50, s59
	v_lshl_add_u32 v42, v34, 2, v6
	v_lshl_add_u32 v52, v51, 2, v6
	v_lshl_add_u32 v54, v53, 2, v6
	v_lshl_add_u32 v56, v55, 2, v6
	v_add_u32_e32 v57, v3, v2
	v_add_u32_e32 v58, v3, v8
	v_add_u32_e32 v59, v3, v9
	v_add_u32_e32 v60, v3, v10
	v_add_u32_e32 v61, v3, v11
	v_add_u32_e32 v62, v3, v12
	v_add_u32_e32 v63, v3, v13
	v_add_u32_e32 v64, v3, v4
	s_mov_b32 s48, s19
	s_mov_b32 s49, s2
	s_branch .LBB0_30

; __device__ __forceinline__ float bflo(unsigned u) { return __uint_as_float(u << 16); }
; __device__ __forceinline__ float bfhi(unsigned u) { return __uint_as_float(u & 0xffff0000u); }
; __device__ __forceinline__ void compress_phase(const bf16_t* __restrict__ proj, const float* __restrict__ pos_k, ...
;     ...
;   for (int it = blockIdx.x; it < 256; it += gridDim.x) {
;     const int kv = it >> 7, b = (it >> 6) & 1, g = (it >> 4) & 3, ntile = it & 15;
;     const float* pos = kv ? pos_v : pos_k;
;     const int off = kv ? OFF_VC : OFF_KC;
;     const bf16_t* w1t = W1T + (size_t)kv * 128 * 4096;
;     const bf16_t* w2t = W2T + (size_t)kv * 128 * 128;
;     const int n0 = ntile * 16;
;     const int n = n0 + c;
;     const bool rowvalid = n < 255;
;     f32x4 acc[8];
; #pragma unroll
;     for (int i = 0; i < 8; ++i) acc[i] = (f32x4){0.f, 0.f, 0.f, 0.f};
;     for (int ks = 0; ks < 16; ++ks) {
;       const int l = w * 4 + (ks >> 2), d0 = (ks & 3) * 32 + quad * 8;
;       bf16x8 a = (bf16x8){0, 0, 0, 0, 0, 0, 0, 0};
;       if (rowvalid) {
;         size_t tokrow = (size_t)b * SEQ + n * 16 + l;
;         uint4 raw = *(const uint4*)(proj + tokrow * NPAD + off + g * 128 + d0);
;         float4 p0 = *(const float4*)(pos + l * 128 + d0), p1 = *(const float4*)(pos + l * 128 + d0 + 4);
;         uint4 pk;
;         pk.x = pack2(bflo(raw.x) + p0.x, bfhi(raw.x) + p0.y);
;         pk.y = pack2(bflo(raw.y) + p0.z, bfhi(raw.y) + p0.w);
;         pk.z = pack2(bflo(raw.z) + p1.x, bfhi(raw.z) + p1.y);
;         pk.w = pack2(bflo(raw.w) + p1.z, bfhi(raw.w) + p1.w);
;         a = *reinterpret_cast<bf16x8*>(&pk);
;       }
; #pragma unroll
;       for (int nt = 0; nt < 8; ++nt) {
;         bf16x8 bw = *(const bf16x8*)(w1t + (size_t)(nt * 16 + c) * 4096 + l * 128 + d0);
;         acc[nt] = __builtin_amdgcn_mfma_f32_16x16x32_bf16(a, bw, acc[nt], 0, 0, 0);
;       }
;     }
.LBB0_211:
	s_ashr_i32 s30, s57, 7
	s_ashr_i32 s31, s30, 31
	s_lshr_b32 s58, s57, 6
	s_lshl_b64 s[8:9], s[30:31], 20
	s_add_u32 s34, s43, s8
	s_addc_u32 s35, s44, s9
	s_lshl_b32 s8, s57, 4
	s_and_b32 s28, s8, 0xf0
	s_bfe_u32 s59, s57, 0x10006
	s_bfe_u32 s36, s57, 0x20004
	s_cmpk_lt_u32 s57, 0x80
	s_cselect_b64 s[8:9], -1, 0
	s_and_b64 s[10:11], s[8:9], exec
	s_cselect_b32 s10, s46, 0x5400
	s_cselect_b32 s62, s13, s15
	s_cselect_b32 s63, s12, s14
	s_add_u32 s10, s25, s10
	s_addc_u32 s11, s42, 0
	s_lshl_b32 s37, s59, 12
	s_lshl_b32 s61, s36, 7
	s_lshl_b32 s60, s36, 8
	v_or_b32_e32 v0, s28, v49
	s_add_u32 s36, s10, s60
	v_cmp_ne_u32_e32 vcc, s24, v0
	v_lshl_or_b32 v46, v0, 4, s37
	v_mov_b32_e32 v47, v37
	s_addc_u32 s37, s11, 0
	s_mov_b32 s64, 0
	s_mov_b32 s65, 0
	v_mov_b32_e32 v0, v37
	v_mov_b32_e32 v1, v37
	v_mov_b32_e32 v2, v37
	v_mov_b32_e32 v3, v37
	v_mov_b32_e32 v4, v37
	v_mov_b32_e32 v5, v37
	v_mov_b32_e32 v6, v37
	v_mov_b32_e32 v7, v37
	v_mov_b32_e32 v12, v37
	v_mov_b32_e32 v13, v37
	v_mov_b32_e32 v14, v37
	v_mov_b32_e32 v15, v37
	v_mov_b32_e32 v8, v37
	v_mov_b32_e32 v9, v37
	v_mov_b32_e32 v10, v37
	v_mov_b32_e32 v11, v37
	v_mov_b32_e32 v20, v37
	v_mov_b32_e32 v21, v37
	v_mov_b32_e32 v22, v37
	v_mov_b32_e32 v23, v37
	v_mov_b32_e32 v16, v37
	v_mov_b32_e32 v17, v37
	v_mov_b32_e32 v18, v37
	v_mov_b32_e32 v19, v37
	v_mov_b32_e32 v28, v37
	v_mov_b32_e32 v29, v37
	v_mov_b32_e32 v30, v37
	v_mov_b32_e32 v31, v37
	v_mov_b32_e32 v24, v37
	v_mov_b32_e32 v25, v37
	v_mov_b32_e32 v26, v37
	v_mov_b32_e32 v27, v37
	v_lshl_add_u32 v125, v52, 1, v44
	v_add_u32_e32 v126, 0x20000, v125
	v_add_u32_e32 v127, 0x40000, v125
	v_add_u32_e32 v128, 0x60000, v125
	v_add_u32_e32 v129, 0x80000, v125
	v_add_u32_e32 v130, 0xa0000, v125
	v_add_u32_e32 v131, 0xc0000, v125
	v_add_u32_e32 v132, 0xe0000, v125
	v_lshlrev_b32_e32 v133, 2, v52
	s_add_i32 s10, s45, 0
	s_lshl_b32 s11, s10, 8
	s_add_u32 s40, s34, s11
	s_addc_u32 s41, s35, 0
	s_lshl_b32 s11, s10, 9
	s_add_u32 s66, s63, s11
	s_addc_u32 s67, s62, 0
	v_add_u32_e32 v124, s10, v46
	v_mul_u32_u24_e32 v124, s47, v124
	v_lshl_add_u32 v124, v52, 1, v124
	global_load_dwordx4 v[80:83], v124, s[36:37]
	global_load_dwordx4 v[84:87], v133, s[66:67]
	global_load_dwordx4 v[88:91], v133, s[66:67] offset:16
	global_load_dwordx4 v[92:95], v125, s[40:41]
	global_load_dwordx4 v[96:99], v126, s[40:41]
	global_load_dwordx4 v[100:103], v127, s[40:41]
	global_load_dwordx4 v[104:107], v128, s[40:41]
	global_load_dwordx4 v[108:111], v129, s[40:41]
	global_load_dwordx4 v[112:115], v130, s[40:41]
	global_load_dwordx4 v[116:119], v131, s[40:41]
	global_load_dwordx4 v[120:123], v132, s[40:41]
	s_waitcnt vmcnt(8)
	v_lshlrev_b32_e32 v168, 16, v80
	v_and_b32_e32 v169, 0xffff0000, v80
	v_lshlrev_b32_e32 v170, 16, v81
	v_and_b32_e32 v171, 0xffff0000, v81
	v_lshlrev_b32_e32 v172, 16, v82
	v_and_b32_e32 v173, 0xffff0000, v82
	v_lshlrev_b32_e32 v174, 16, v83
	v_and_b32_e32 v175, 0xffff0000, v83
	v_pk_add_f32 v[168:169], v[84:85], v[168:169]
	v_pk_add_f32 v[170:171], v[86:87], v[170:171]
	v_pk_add_f32 v[172:173], v[88:89], v[172:173]
	v_pk_add_f32 v[174:175], v[90:91], v[174:175]
	v_cvt_pk_bf16_f32 v32, v168, v169
	v_cvt_pk_bf16_f32 v33, v170, v171
	v_cvt_pk_bf16_f32 v34, v172, v173
	v_cvt_pk_bf16_f32 v35, v174, v175
	v_cndmask_b32_e32 v32, 0, v32, vcc
	v_cndmask_b32_e32 v33, 0, v33, vcc
	v_cndmask_b32_e32 v34, 0, v34, vcc
	v_cndmask_b32_e32 v35, 0, v35, vcc
	global_load_dwordx4 v[80:83], v124, s[36:37] offset:64
	global_load_dwordx4 v[84:87], v133, s[66:67] offset:128
	global_load_dwordx4 v[88:91], v133, s[66:67] offset:144
	global_load_dwordx4 v[136:139], v125, s[40:41] offset:64
	global_load_dwordx4 v[140:143], v126, s[40:41] offset:64
	global_load_dwordx4 v[144:147], v127, s[40:41] offset:64
	global_load_dwordx4 v[148:151], v128, s[40:41] offset:64
	global_load_dwordx4 v[152:155], v129, s[40:41] offset:64
	global_load_dwordx4 v[156:159], v130, s[40:41] offset:64
	global_load_dwordx4 v[160:163], v131, s[40:41] offset:64
	global_load_dwordx4 v[164:167], v132, s[40:41] offset:64
	s_waitcnt vmcnt(18)
	v_mfma_f32_16x16x32_bf16 v[4:7], v[32:35], v[92:95], v[4:7]
	s_waitcnt vmcnt(17)
	v_mfma_f32_16x16x32_bf16 v[12:15], v[32:35], v[96:99], v[12:15]
	s_waitcnt vmcnt(16)
	v_mfma_f32_16x16x32_bf16 v[8:11], v[32:35], v[100:103], v[8:11]
	s_waitcnt vmcnt(15)
	v_mfma_f32_16x16x32_bf16 v[20:23], v[32:35], v[104:107], v[20:23]
	s_waitcnt vmcnt(14)
	v_mfma_f32_16x16x32_bf16 v[16:19], v[32:35], v[108:111], v[16:19]
	s_waitcnt vmcnt(13)
	v_mfma_f32_16x16x32_bf16 v[28:31], v[32:35], v[112:115], v[28:31]
	s_waitcnt vmcnt(12)
	v_mfma_f32_16x16x32_bf16 v[24:27], v[32:35], v[116:119], v[24:27]
	s_waitcnt vmcnt(11)
	v_mfma_f32_16x16x32_bf16 v[0:3], v[32:35], v[120:123], v[0:3]
	s_waitcnt vmcnt(8)
	v_lshlrev_b32_e32 v168, 16, v80
	v_and_b32_e32 v169, 0xffff0000, v80
	v_lshlrev_b32_e32 v170, 16, v81
	v_and_b32_e32 v171, 0xffff0000, v81
	v_lshlrev_b32_e32 v172, 16, v82
	v_and_b32_e32 v173, 0xffff0000, v82
	v_lshlrev_b32_e32 v174, 16, v83
	v_and_b32_e32 v175, 0xffff0000, v83
	v_pk_add_f32 v[168:169], v[84:85], v[168:169]
	v_pk_add_f32 v[170:171], v[86:87], v[170:171]
	v_pk_add_f32 v[172:173], v[88:89], v[172:173]
	v_pk_add_f32 v[174:175], v[90:91], v[174:175]
	v_cvt_pk_bf16_f32 v32, v168, v169
	v_cvt_pk_bf16_f32 v33, v170, v171
	v_cvt_pk_bf16_f32 v34, v172, v173
	v_cvt_pk_bf16_f32 v35, v174, v175
	v_cndmask_b32_e32 v32, 0, v32, vcc
	v_cndmask_b32_e32 v33, 0, v33, vcc
	v_cndmask_b32_e32 v34, 0, v34, vcc
	v_cndmask_b32_e32 v35, 0, v35, vcc
	global_load_dwordx4 v[80:83], v124, s[36:37] offset:128
	global_load_dwordx4 v[84:87], v133, s[66:67] offset:256
	global_load_dwordx4 v[88:91], v133, s[66:67] offset:272
	global_load_dwordx4 v[92:95], v125, s[40:41] offset:128
	global_load_dwordx4 v[96:99], v126, s[40:41] offset:128
	global_load_dwordx4 v[100:103], v127, s[40:41] offset:128
	global_load_dwordx4 v[104:107], v128, s[40:41] offset:128
	global_load_dwordx4 v[108:111], v129, s[40:41] offset:128
	global_load_dwordx4 v[112:115], v130, s[40:41] offset:128
	global_load_dwordx4 v[116:119], v131, s[40:41] offset:128
	global_load_dwordx4 v[120:123], v132, s[40:41] offset:128
	s_waitcnt vmcnt(18)
; __device__ __forceinline__ float bflo(unsigned u) { return __uint_as_float(u << 16); }
; __device__ __forceinline__ float bfhi(unsigned u) { return __uint_as_float(u & 0xffff0000u); }
; __device__ __forceinline__ void compress_phase(const bf16_t* __restrict__ proj, const float* __restrict__ pos_k, ...
;     ...
;     for (int ks = 0; ks < 16; ++ks) {
;       const int l = w * 4 + (ks >> 2), d0 = (ks & 3) * 32 + quad * 8;
;       bf16x8 a = (bf16x8){0, 0, 0, 0, 0, 0, 0, 0};
;       if (rowvalid) {
;         size_t tokrow = (size_t)b * SEQ + n * 16 + l;
;         uint4 raw = *(const uint4*)(proj + tokrow * NPAD + off + g * 128 + d0);
;         float4 p0 = *(const float4*)(pos + l * 128 + d0), p1 = *(const float4*)(pos + l * 128 + d0 + 4);
;         uint4 pk;
;         pk.x = pack2(bflo(raw.x) + p0.x, bfhi(raw.x) + p0.y);
;         pk.y = pack2(bflo(raw.y) + p0.z, bfhi(raw.y) + p0.w);
;         pk.z = pack2(bflo(raw.z) + p1.x, bfhi(raw.z) + p1.y);
;         pk.w = pack2(bflo(raw.w) + p1.z, bfhi(raw.w) + p1.w);
;         a = *reinterpret_cast<bf16x8*>(&pk);
;       }
; #pragma unroll
;       for (int nt = 0; nt < 8; ++nt) {
;         bf16x8 bw = *(const bf16x8*)(w1t + (size_t)(nt * 16 + c) * 4096 + l * 128 + d0);
;         acc[nt] = __builtin_amdgcn_mfma_f32_16x16x32_bf16(a, bw, acc[nt], 0, 0, 0);
;       }
;     }
	v_mfma_f32_16x16x32_bf16 v[4:7], v[32:35], v[136:139], v[4:7]
	s_waitcnt vmcnt(17)
	v_mfma_f32_16x16x32_bf16 v[12:15], v[32:35], v[140:143], v[12:15]
	s_waitcnt vmcnt(16)
	v_mfma_f32_16x16x32_bf16 v[8:11], v[32:35], v[144:147], v[8:11]
	s_waitcnt vmcnt(15)
	v_mfma_f32_16x16x32_bf16 v[20:23], v[32:35], v[148:151], v[20:23]
	s_waitcnt vmcnt(14)
	v_mfma_f32_16x16x32_bf16 v[16:19], v[32:35], v[152:155], v[16:19]
	s_waitcnt vmcnt(13)
	v_mfma_f32_16x16x32_bf16 v[28:31], v[32:35], v[156:159], v[28:31]
	s_waitcnt vmcnt(12)
	v_mfma_f32_16x16x32_bf16 v[24:27], v[32:35], v[160:163], v[24:27]
	s_waitcnt vmcnt(11)
	v_mfma_f32_16x16x32_bf16 v[0:3], v[32:35], v[164:167], v[0:3]
	s_waitcnt vmcnt(8)
	v_lshlrev_b32_e32 v168, 16, v80
	v_and_b32_e32 v169, 0xffff0000, v80
	v_lshlrev_b32_e32 v170, 16, v81
	v_and_b32_e32 v171, 0xffff0000, v81
	v_lshlrev_b32_e32 v172, 16, v82
	v_and_b32_e32 v173, 0xffff0000, v82
	v_lshlrev_b32_e32 v174, 16, v83
	v_and_b32_e32 v175, 0xffff0000, v83
	v_pk_add_f32 v[168:169], v[84:85], v[168:169]
	v_pk_add_f32 v[170:171], v[86:87], v[170:171]
	v_pk_add_f32 v[172:173], v[88:89], v[172:173]
	v_pk_add_f32 v[174:175], v[90:91], v[174:175]
	v_cvt_pk_bf16_f32 v32, v168, v169
	v_cvt_pk_bf16_f32 v33, v170, v171
	v_cvt_pk_bf16_f32 v34, v172, v173
	v_cvt_pk_bf16_f32 v35, v174, v175
	v_cndmask_b32_e32 v32, 0, v32, vcc
	v_cndmask_b32_e32 v33, 0, v33, vcc
	v_cndmask_b32_e32 v34, 0, v34, vcc
	v_cndmask_b32_e32 v35, 0, v35, vcc
	global_load_dwordx4 v[80:83], v124, s[36:37] offset:192
	global_load_dwordx4 v[84:87], v133, s[66:67] offset:384
	global_load_dwordx4 v[88:91], v133, s[66:67] offset:400
	global_load_dwordx4 v[136:139], v125, s[40:41] offset:192
	global_load_dwordx4 v[140:143], v126, s[40:41] offset:192
	global_load_dwordx4 v[144:147], v127, s[40:41] offset:192
	global_load_dwordx4 v[148:151], v128, s[40:41] offset:192
	global_load_dwordx4 v[152:155], v129, s[40:41] offset:192
	global_load_dwordx4 v[156:159], v130, s[40:41] offset:192
	global_load_dwordx4 v[160:163], v131, s[40:41] offset:192
	global_load_dwordx4 v[164:167], v132, s[40:41] offset:192
	s_waitcnt vmcnt(18)
	v_mfma_f32_16x16x32_bf16 v[4:7], v[32:35], v[92:95], v[4:7]
	s_waitcnt vmcnt(17)
	v_mfma_f32_16x16x32_bf16 v[12:15], v[32:35], v[96:99], v[12:15]
	s_waitcnt vmcnt(16)
	v_mfma_f32_16x16x32_bf16 v[8:11], v[32:35], v[100:103], v[8:11]
	s_waitcnt vmcnt(15)
	v_mfma_f32_16x16x32_bf16 v[20:23], v[32:35], v[104:107], v[20:23]
	s_waitcnt vmcnt(14)
	v_mfma_f32_16x16x32_bf16 v[16:19], v[32:35], v[108:111], v[16:19]
	s_waitcnt vmcnt(13)
	v_mfma_f32_16x16x32_bf16 v[28:31], v[32:35], v[112:115], v[28:31]
	s_waitcnt vmcnt(12)
	v_mfma_f32_16x16x32_bf16 v[24:27], v[32:35], v[116:119], v[24:27]
	s_waitcnt vmcnt(11)
	v_mfma_f32_16x16x32_bf16 v[0:3], v[32:35], v[120:123], v[0:3]
	s_waitcnt vmcnt(8)
	v_lshlrev_b32_e32 v168, 16, v80
	v_and_b32_e32 v169, 0xffff0000, v80
	v_lshlrev_b32_e32 v170, 16, v81
	v_and_b32_e32 v171, 0xffff0000, v81
	v_lshlrev_b32_e32 v172, 16, v82
	v_and_b32_e32 v173, 0xffff0000, v82
	v_lshlrev_b32_e32 v174, 16, v83
	v_and_b32_e32 v175, 0xffff0000, v83
	v_pk_add_f32 v[168:169], v[84:85], v[168:169]
	v_pk_add_f32 v[170:171], v[86:87], v[170:171]
	v_pk_add_f32 v[172:173], v[88:89], v[172:173]
	v_pk_add_f32 v[174:175], v[90:91], v[174:175]
	v_cvt_pk_bf16_f32 v32, v168, v169
	v_cvt_pk_bf16_f32 v33, v170, v171
	v_cvt_pk_bf16_f32 v34, v172, v173
	v_cvt_pk_bf16_f32 v35, v174, v175
	v_cndmask_b32_e32 v32, 0, v32, vcc
	v_cndmask_b32_e32 v33, 0, v33, vcc
	v_cndmask_b32_e32 v34, 0, v34, vcc
	v_cndmask_b32_e32 v35, 0, v35, vcc
	s_add_i32 s10, s45, 1
	s_lshl_b32 s11, s10, 8
	s_add_u32 s40, s34, s11
	s_addc_u32 s41, s35, 0
	s_lshl_b32 s11, s10, 9
	s_add_u32 s66, s63, s11
	s_addc_u32 s67, s62, 0
	v_add_u32_e32 v124, s10, v46
	v_mul_u32_u24_e32 v124, s47, v124
	v_lshl_add_u32 v124, v52, 1, v124
	global_load_dwordx4 v[80:83], v124, s[36:37]
	global_load_dwordx4 v[84:87], v133, s[66:67]
	global_load_dwordx4 v[88:91], v133, s[66:67] offset:16
	global_load_dwordx4 v[92:95], v125, s[40:41]
	global_load_dwordx4 v[96:99], v126, s[40:41]
	global_load_dwordx4 v[100:103], v127, s[40:41]
	global_load_dwordx4 v[104:107], v128, s[40:41]
	global_load_dwordx4 v[108:111], v129, s[40:41]
	global_load_dwordx4 v[112:115], v130, s[40:41]
	global_load_dwordx4 v[116:119], v131, s[40:41]
	global_load_dwordx4 v[120:123], v132, s[40:41]
	s_waitcnt vmcnt(18)
	v_mfma_f32_16x16x32_bf16 v[4:7], v[32:35], v[136:139], v[4:7]
	s_waitcnt vmcnt(17)
	v_mfma_f32_16x16x32_bf16 v[12:15], v[32:35], v[140:143], v[12:15]
	s_waitcnt vmcnt(16)
	v_mfma_f32_16x16x32_bf16 v[8:11], v[32:35], v[144:147], v[8:11]
	s_waitcnt vmcnt(15)
	v_mfma_f32_16x16x32_bf16 v[20:23], v[32:35], v[148:151], v[20:23]
	s_waitcnt vmcnt(14)
	v_mfma_f32_16x16x32_bf16 v[16:19], v[32:35], v[152:155], v[16:19]
	s_waitcnt vmcnt(13)
	v_mfma_f32_16x16x32_bf16 v[28:31], v[32:35], v[156:159], v[28:31]
	s_waitcnt vmcnt(12)
	v_mfma_f32_16x16x32_bf16 v[24:27], v[32:35], v[160:163], v[24:27]
	s_waitcnt vmcnt(11)
	v_mfma_f32_16x16x32_bf16 v[0:3], v[32:35], v[164:167], v[0:3]
	s_waitcnt vmcnt(8)
; __device__ __forceinline__ float bflo(unsigned u) { return __uint_as_float(u << 16); }
; __device__ __forceinline__ float bfhi(unsigned u) { return __uint_as_float(u & 0xffff0000u); }
; __device__ __forceinline__ void compress_phase(const bf16_t* __restrict__ proj, const float* __restrict__ pos_k, ...
;     ...
;     for (int ks = 0; ks < 16; ++ks) {
;       const int l = w * 4 + (ks >> 2), d0 = (ks & 3) * 32 + quad * 8;
;       bf16x8 a = (bf16x8){0, 0, 0, 0, 0, 0, 0, 0};
;       if (rowvalid) {
;         size_t tokrow = (size_t)b * SEQ + n * 16 + l;
;         uint4 raw = *(const uint4*)(proj + tokrow * NPAD + off + g * 128 + d0);
;         float4 p0 = *(const float4*)(pos + l * 128 + d0), p1 = *(const float4*)(pos + l * 128 + d0 + 4);
;         uint4 pk;
;         pk.x = pack2(bflo(raw.x) + p0.x, bfhi(raw.x) + p0.y);
;         pk.y = pack2(bflo(raw.y) + p0.z, bfhi(raw.y) + p0.w);
;         pk.z = pack2(bflo(raw.z) + p1.x, bfhi(raw.z) + p1.y);
;         pk.w = pack2(bflo(raw.w) + p1.z, bfhi(raw.w) + p1.w);
;         a = *reinterpret_cast<bf16x8*>(&pk);
;       }
; #pragma unroll
;       for (int nt = 0; nt < 8; ++nt) {
;         bf16x8 bw = *(const bf16x8*)(w1t + (size_t)(nt * 16 + c) * 4096 + l * 128 + d0);
;         acc[nt] = __builtin_amdgcn_mfma_f32_16x16x32_bf16(a, bw, acc[nt], 0, 0, 0);
;       }
;     }
	v_lshlrev_b32_e32 v168, 16, v80
	v_and_b32_e32 v169, 0xffff0000, v80
	v_lshlrev_b32_e32 v170, 16, v81
	v_and_b32_e32 v171, 0xffff0000, v81
	v_lshlrev_b32_e32 v172, 16, v82
	v_and_b32_e32 v173, 0xffff0000, v82
	v_lshlrev_b32_e32 v174, 16, v83
	v_and_b32_e32 v175, 0xffff0000, v83
	v_pk_add_f32 v[168:169], v[84:85], v[168:169]
	v_pk_add_f32 v[170:171], v[86:87], v[170:171]
	v_pk_add_f32 v[172:173], v[88:89], v[172:173]
	v_pk_add_f32 v[174:175], v[90:91], v[174:175]
	v_cvt_pk_bf16_f32 v32, v168, v169
	v_cvt_pk_bf16_f32 v33, v170, v171
	v_cvt_pk_bf16_f32 v34, v172, v173
	v_cvt_pk_bf16_f32 v35, v174, v175
	v_cndmask_b32_e32 v32, 0, v32, vcc
	v_cndmask_b32_e32 v33, 0, v33, vcc
	v_cndmask_b32_e32 v34, 0, v34, vcc
	v_cndmask_b32_e32 v35, 0, v35, vcc
	global_load_dwordx4 v[80:83], v124, s[36:37] offset:64
	global_load_dwordx4 v[84:87], v133, s[66:67] offset:128
	global_load_dwordx4 v[88:91], v133, s[66:67] offset:144
	global_load_dwordx4 v[136:139], v125, s[40:41] offset:64
	global_load_dwordx4 v[140:143], v126, s[40:41] offset:64
	global_load_dwordx4 v[144:147], v127, s[40:41] offset:64
	global_load_dwordx4 v[148:151], v128, s[40:41] offset:64
	global_load_dwordx4 v[152:155], v129, s[40:41] offset:64
	global_load_dwordx4 v[156:159], v130, s[40:41] offset:64
	global_load_dwordx4 v[160:163], v131, s[40:41] offset:64
	global_load_dwordx4 v[164:167], v132, s[40:41] offset:64
	s_waitcnt vmcnt(18)
	v_mfma_f32_16x16x32_bf16 v[4:7], v[32:35], v[92:95], v[4:7]
	s_waitcnt vmcnt(17)
	v_mfma_f32_16x16x32_bf16 v[12:15], v[32:35], v[96:99], v[12:15]
	s_waitcnt vmcnt(16)
	v_mfma_f32_16x16x32_bf16 v[8:11], v[32:35], v[100:103], v[8:11]
	s_waitcnt vmcnt(15)
	v_mfma_f32_16x16x32_bf16 v[20:23], v[32:35], v[104:107], v[20:23]
	s_waitcnt vmcnt(14)
	v_mfma_f32_16x16x32_bf16 v[16:19], v[32:35], v[108:111], v[16:19]
	s_waitcnt vmcnt(13)
	v_mfma_f32_16x16x32_bf16 v[28:31], v[32:35], v[112:115], v[28:31]
	s_waitcnt vmcnt(12)
	v_mfma_f32_16x16x32_bf16 v[24:27], v[32:35], v[116:119], v[24:27]
	s_waitcnt vmcnt(11)
	v_mfma_f32_16x16x32_bf16 v[0:3], v[32:35], v[120:123], v[0:3]
	s_waitcnt vmcnt(8)
	v_lshlrev_b32_e32 v168, 16, v80
	v_and_b32_e32 v169, 0xffff0000, v80
	v_lshlrev_b32_e32 v170, 16, v81
	v_and_b32_e32 v171, 0xffff0000, v81
	v_lshlrev_b32_e32 v172, 16, v82
	v_and_b32_e32 v173, 0xffff0000, v82
	v_lshlrev_b32_e32 v174, 16, v83
	v_and_b32_e32 v175, 0xffff0000, v83
	v_pk_add_f32 v[168:169], v[84:85], v[168:169]
	v_pk_add_f32 v[170:171], v[86:87], v[170:171]
	v_pk_add_f32 v[172:173], v[88:89], v[172:173]
	v_pk_add_f32 v[174:175], v[90:91], v[174:175]
	v_cvt_pk_bf16_f32 v32, v168, v169
	v_cvt_pk_bf16_f32 v33, v170, v171
	v_cvt_pk_bf16_f32 v34, v172, v173
	v_cvt_pk_bf16_f32 v35, v174, v175
	v_cndmask_b32_e32 v32, 0, v32, vcc
	v_cndmask_b32_e32 v33, 0, v33, vcc
	v_cndmask_b32_e32 v34, 0, v34, vcc
	v_cndmask_b32_e32 v35, 0, v35, vcc
	global_load_dwordx4 v[80:83], v124, s[36:37] offset:128
	global_load_dwordx4 v[84:87], v133, s[66:67] offset:256
	global_load_dwordx4 v[88:91], v133, s[66:67] offset:272
	global_load_dwordx4 v[92:95], v125, s[40:41] offset:128
	global_load_dwordx4 v[96:99], v126, s[40:41] offset:128
	global_load_dwordx4 v[100:103], v127, s[40:41] offset:128
	global_load_dwordx4 v[104:107], v128, s[40:41] offset:128
	global_load_dwordx4 v[108:111], v129, s[40:41] offset:128
	global_load_dwordx4 v[112:115], v130, s[40:41] offset:128
	global_load_dwordx4 v[116:119], v131, s[40:41] offset:128
	global_load_dwordx4 v[120:123], v132, s[40:41] offset:128
	s_waitcnt vmcnt(18)
	v_mfma_f32_16x16x32_bf16 v[4:7], v[32:35], v[136:139], v[4:7]
	s_waitcnt vmcnt(17)
	v_mfma_f32_16x16x32_bf16 v[12:15], v[32:35], v[140:143], v[12:15]
	s_waitcnt vmcnt(16)
	v_mfma_f32_16x16x32_bf16 v[8:11], v[32:35], v[144:147], v[8:11]
	s_waitcnt vmcnt(15)
	v_mfma_f32_16x16x32_bf16 v[20:23], v[32:35], v[148:151], v[20:23]
	s_waitcnt vmcnt(14)
	v_mfma_f32_16x16x32_bf16 v[16:19], v[32:35], v[152:155], v[16:19]
	s_waitcnt vmcnt(13)
	v_mfma_f32_16x16x32_bf16 v[28:31], v[32:35], v[156:159], v[28:31]
	s_waitcnt vmcnt(12)
	v_mfma_f32_16x16x32_bf16 v[24:27], v[32:35], v[160:163], v[24:27]
	s_waitcnt vmcnt(11)
	v_mfma_f32_16x16x32_bf16 v[0:3], v[32:35], v[164:167], v[0:3]
	s_waitcnt vmcnt(8)
	v_lshlrev_b32_e32 v168, 16, v80
	v_and_b32_e32 v169, 0xffff0000, v80
	v_lshlrev_b32_e32 v170, 16, v81
	v_and_b32_e32 v171, 0xffff0000, v81
	v_lshlrev_b32_e32 v172, 16, v82
	v_and_b32_e32 v173, 0xffff0000, v82
	v_lshlrev_b32_e32 v174, 16, v83
	v_and_b32_e32 v175, 0xffff0000, v83
	v_pk_add_f32 v[168:169], v[84:85], v[168:169]
	v_pk_add_f32 v[170:171], v[86:87], v[170:171]
	v_pk_add_f32 v[172:173], v[88:89], v[172:173]
	v_pk_add_f32 v[174:175], v[90:91], v[174:175]
	v_cvt_pk_bf16_f32 v32, v168, v169
	v_cvt_pk_bf16_f32 v33, v170, v171
	v_cvt_pk_bf16_f32 v34, v172, v173
	v_cvt_pk_bf16_f32 v35, v174, v175
	v_cndmask_b32_e32 v32, 0, v32, vcc
	v_cndmask_b32_e32 v33, 0, v33, vcc
	v_cndmask_b32_e32 v34, 0, v34, vcc
	v_cndmask_b32_e32 v35, 0, v35, vcc
	global_load_dwordx4 v[80:83], v124, s[36:37] offset:192
	global_load_dwordx4 v[84:87], v133, s[66:67] offset:384
	global_load_dwordx4 v[88:91], v133, s[66:67] offset:400
	global_load_dwordx4 v[136:139], v125, s[40:41] offset:192
	global_load_dwordx4 v[140:143], v126, s[40:41] offset:192
	global_load_dwordx4 v[144:147], v127, s[40:41] offset:192
	global_load_dwordx4 v[148:151], v128, s[40:41] offset:192
	global_load_dwordx4 v[152:155], v129, s[40:41] offset:192
	global_load_dwordx4 v[156:159], v130, s[40:41] offset:192
	global_load_dwordx4 v[160:163], v131, s[40:41] offset:192
	global_load_dwordx4 v[164:167], v132, s[40:41] offset:192
	s_waitcnt vmcnt(18)
; __device__ __forceinline__ float bflo(unsigned u) { return __uint_as_float(u << 16); }
; __device__ __forceinline__ float bfhi(unsigned u) { return __uint_as_float(u & 0xffff0000u); }
; __device__ __forceinline__ void compress_phase(const bf16_t* __restrict__ proj, const float* __restrict__ pos_k, ...
;     ...
;     for (int ks = 0; ks < 16; ++ks) {
;       const int l = w * 4 + (ks >> 2), d0 = (ks & 3) * 32 + quad * 8;
;       bf16x8 a = (bf16x8){0, 0, 0, 0, 0, 0, 0, 0};
;       if (rowvalid) {
;         size_t tokrow = (size_t)b * SEQ + n * 16 + l;
;         uint4 raw = *(const uint4*)(proj + tokrow * NPAD + off + g * 128 + d0);
;         float4 p0 = *(const float4*)(pos + l * 128 + d0), p1 = *(const float4*)(pos + l * 128 + d0 + 4);
;         uint4 pk;
;         pk.x = pack2(bflo(raw.x) + p0.x, bfhi(raw.x) + p0.y);
;         pk.y = pack2(bflo(raw.y) + p0.z, bfhi(raw.y) + p0.w);
;         pk.z = pack2(bflo(raw.z) + p1.x, bfhi(raw.z) + p1.y);
;         pk.w = pack2(bflo(raw.w) + p1.z, bfhi(raw.w) + p1.w);
;         a = *reinterpret_cast<bf16x8*>(&pk);
;       }
; #pragma unroll
;       for (int nt = 0; nt < 8; ++nt) {
;         bf16x8 bw = *(const bf16x8*)(w1t + (size_t)(nt * 16 + c) * 4096 + l * 128 + d0);
;         acc[nt] = __builtin_amdgcn_mfma_f32_16x16x32_bf16(a, bw, acc[nt], 0, 0, 0);
;       }
;     }
	v_mfma_f32_16x16x32_bf16 v[4:7], v[32:35], v[92:95], v[4:7]
	s_waitcnt vmcnt(17)
	v_mfma_f32_16x16x32_bf16 v[12:15], v[32:35], v[96:99], v[12:15]
	s_waitcnt vmcnt(16)
	v_mfma_f32_16x16x32_bf16 v[8:11], v[32:35], v[100:103], v[8:11]
	s_waitcnt vmcnt(15)
	v_mfma_f32_16x16x32_bf16 v[20:23], v[32:35], v[104:107], v[20:23]
	s_waitcnt vmcnt(14)
	v_mfma_f32_16x16x32_bf16 v[16:19], v[32:35], v[108:111], v[16:19]
	s_waitcnt vmcnt(13)
	v_mfma_f32_16x16x32_bf16 v[28:31], v[32:35], v[112:115], v[28:31]
	s_waitcnt vmcnt(12)
	v_mfma_f32_16x16x32_bf16 v[24:27], v[32:35], v[116:119], v[24:27]
	s_waitcnt vmcnt(11)
	v_mfma_f32_16x16x32_bf16 v[0:3], v[32:35], v[120:123], v[0:3]
	s_waitcnt vmcnt(8)
	v_lshlrev_b32_e32 v168, 16, v80
	v_and_b32_e32 v169, 0xffff0000, v80
	v_lshlrev_b32_e32 v170, 16, v81
	v_and_b32_e32 v171, 0xffff0000, v81
	v_lshlrev_b32_e32 v172, 16, v82
	v_and_b32_e32 v173, 0xffff0000, v82
	v_lshlrev_b32_e32 v174, 16, v83
	v_and_b32_e32 v175, 0xffff0000, v83
	v_pk_add_f32 v[168:169], v[84:85], v[168:169]
	v_pk_add_f32 v[170:171], v[86:87], v[170:171]
	v_pk_add_f32 v[172:173], v[88:89], v[172:173]
	v_pk_add_f32 v[174:175], v[90:91], v[174:175]
	v_cvt_pk_bf16_f32 v32, v168, v169
	v_cvt_pk_bf16_f32 v33, v170, v171
	v_cvt_pk_bf16_f32 v34, v172, v173
	v_cvt_pk_bf16_f32 v35, v174, v175
	v_cndmask_b32_e32 v32, 0, v32, vcc
	v_cndmask_b32_e32 v33, 0, v33, vcc
	v_cndmask_b32_e32 v34, 0, v34, vcc
	v_cndmask_b32_e32 v35, 0, v35, vcc
	s_add_i32 s10, s45, 2
	s_lshl_b32 s11, s10, 8
	s_add_u32 s40, s34, s11
	s_addc_u32 s41, s35, 0
	s_lshl_b32 s11, s10, 9
	s_add_u32 s66, s63, s11
	s_addc_u32 s67, s62, 0
	v_add_u32_e32 v124, s10, v46
	v_mul_u32_u24_e32 v124, s47, v124
	v_lshl_add_u32 v124, v52, 1, v124
	global_load_dwordx4 v[80:83], v124, s[36:37]
	global_load_dwordx4 v[84:87], v133, s[66:67]
	global_load_dwordx4 v[88:91], v133, s[66:67] offset:16
	global_load_dwordx4 v[92:95], v125, s[40:41]
	global_load_dwordx4 v[96:99], v126, s[40:41]
	global_load_dwordx4 v[100:103], v127, s[40:41]
	global_load_dwordx4 v[104:107], v128, s[40:41]
	global_load_dwordx4 v[108:111], v129, s[40:41]
	global_load_dwordx4 v[112:115], v130, s[40:41]
	global_load_dwordx4 v[116:119], v131, s[40:41]
	global_load_dwordx4 v[120:123], v132, s[40:41]
	s_waitcnt vmcnt(18)
	v_mfma_f32_16x16x32_bf16 v[4:7], v[32:35], v[136:139], v[4:7]
	s_waitcnt vmcnt(17)
	v_mfma_f32_16x16x32_bf16 v[12:15], v[32:35], v[140:143], v[12:15]
	s_waitcnt vmcnt(16)
	v_mfma_f32_16x16x32_bf16 v[8:11], v[32:35], v[144:147], v[8:11]
	s_waitcnt vmcnt(15)
	v_mfma_f32_16x16x32_bf16 v[20:23], v[32:35], v[148:151], v[20:23]
	s_waitcnt vmcnt(14)
	v_mfma_f32_16x16x32_bf16 v[16:19], v[32:35], v[152:155], v[16:19]
	s_waitcnt vmcnt(13)
	v_mfma_f32_16x16x32_bf16 v[28:31], v[32:35], v[156:159], v[28:31]
	s_waitcnt vmcnt(12)
	v_mfma_f32_16x16x32_bf16 v[24:27], v[32:35], v[160:163], v[24:27]
	s_waitcnt vmcnt(11)
	v_mfma_f32_16x16x32_bf16 v[0:3], v[32:35], v[164:167], v[0:3]
	s_waitcnt vmcnt(8)
	v_lshlrev_b32_e32 v168, 16, v80
	v_and_b32_e32 v169, 0xffff0000, v80
	v_lshlrev_b32_e32 v170, 16, v81
	v_and_b32_e32 v171, 0xffff0000, v81
	v_lshlrev_b32_e32 v172, 16, v82
	v_and_b32_e32 v173, 0xffff0000, v82
	v_lshlrev_b32_e32 v174, 16, v83
	v_and_b32_e32 v175, 0xffff0000, v83
	v_pk_add_f32 v[168:169], v[84:85], v[168:169]
	v_pk_add_f32 v[170:171], v[86:87], v[170:171]
	v_pk_add_f32 v[172:173], v[88:89], v[172:173]
	v_pk_add_f32 v[174:175], v[90:91], v[174:175]
	v_cvt_pk_bf16_f32 v32, v168, v169
	v_cvt_pk_bf16_f32 v33, v170, v171
	v_cvt_pk_bf16_f32 v34, v172, v173
	v_cvt_pk_bf16_f32 v35, v174, v175
	v_cndmask_b32_e32 v32, 0, v32, vcc
	v_cndmask_b32_e32 v33, 0, v33, vcc
	v_cndmask_b32_e32 v34, 0, v34, vcc
	v_cndmask_b32_e32 v35, 0, v35, vcc
	global_load_dwordx4 v[80:83], v124, s[36:37] offset:64
	global_load_dwordx4 v[84:87], v133, s[66:67] offset:128
	global_load_dwordx4 v[88:91], v133, s[66:67] offset:144
	global_load_dwordx4 v[136:139], v125, s[40:41] offset:64
	global_load_dwordx4 v[140:143], v126, s[40:41] offset:64
	global_load_dwordx4 v[144:147], v127, s[40:41] offset:64
	global_load_dwordx4 v[148:151], v128, s[40:41] offset:64
	global_load_dwordx4 v[152:155], v129, s[40:41] offset:64
	global_load_dwordx4 v[156:159], v130, s[40:41] offset:64
	global_load_dwordx4 v[160:163], v131, s[40:41] offset:64
	global_load_dwordx4 v[164:167], v132, s[40:41] offset:64
	s_waitcnt vmcnt(18)
	v_mfma_f32_16x16x32_bf16 v[4:7], v[32:35], v[92:95], v[4:7]
	s_waitcnt vmcnt(17)
	v_mfma_f32_16x16x32_bf16 v[12:15], v[32:35], v[96:99], v[12:15]
	s_waitcnt vmcnt(16)
	v_mfma_f32_16x16x32_bf16 v[8:11], v[32:35], v[100:103], v[8:11]
	s_waitcnt vmcnt(15)
	v_mfma_f32_16x16x32_bf16 v[20:23], v[32:35], v[104:107], v[20:23]
	s_waitcnt vmcnt(14)
	v_mfma_f32_16x16x32_bf16 v[16:19], v[32:35], v[108:111], v[16:19]
	s_waitcnt vmcnt(13)
	v_mfma_f32_16x16x32_bf16 v[28:31], v[32:35], v[112:115], v[28:31]
	s_waitcnt vmcnt(12)
	v_mfma_f32_16x16x32_bf16 v[24:27], v[32:35], v[116:119], v[24:27]
	s_waitcnt vmcnt(11)
	v_mfma_f32_16x16x32_bf16 v[0:3], v[32:35], v[120:123], v[0:3]
	s_waitcnt vmcnt(8)
; __device__ __forceinline__ float bflo(unsigned u) { return __uint_as_float(u << 16); }
; __device__ __forceinline__ float bfhi(unsigned u) { return __uint_as_float(u & 0xffff0000u); }
; __device__ __forceinline__ void compress_phase(const bf16_t* __restrict__ proj, const float* __restrict__ pos_k, ...
;     ...
;     for (int ks = 0; ks < 16; ++ks) {
;       const int l = w * 4 + (ks >> 2), d0 = (ks & 3) * 32 + quad * 8;
;       bf16x8 a = (bf16x8){0, 0, 0, 0, 0, 0, 0, 0};
;       if (rowvalid) {
;         size_t tokrow = (size_t)b * SEQ + n * 16 + l;
;         uint4 raw = *(const uint4*)(proj + tokrow * NPAD + off + g * 128 + d0);
;         float4 p0 = *(const float4*)(pos + l * 128 + d0), p1 = *(const float4*)(pos + l * 128 + d0 + 4);
;         uint4 pk;
;         pk.x = pack2(bflo(raw.x) + p0.x, bfhi(raw.x) + p0.y);
;         pk.y = pack2(bflo(raw.y) + p0.z, bfhi(raw.y) + p0.w);
;         pk.z = pack2(bflo(raw.z) + p1.x, bfhi(raw.z) + p1.y);
;         pk.w = pack2(bflo(raw.w) + p1.z, bfhi(raw.w) + p1.w);
;         a = *reinterpret_cast<bf16x8*>(&pk);
;       }
; #pragma unroll
;       for (int nt = 0; nt < 8; ++nt) {
;         bf16x8 bw = *(const bf16x8*)(w1t + (size_t)(nt * 16 + c) * 4096 + l * 128 + d0);
;         acc[nt] = __builtin_amdgcn_mfma_f32_16x16x32_bf16(a, bw, acc[nt], 0, 0, 0);
;       }
;     }
	v_lshlrev_b32_e32 v168, 16, v80
	v_and_b32_e32 v169, 0xffff0000, v80
	v_lshlrev_b32_e32 v170, 16, v81
	v_and_b32_e32 v171, 0xffff0000, v81
	v_lshlrev_b32_e32 v172, 16, v82
	v_and_b32_e32 v173, 0xffff0000, v82
	v_lshlrev_b32_e32 v174, 16, v83
	v_and_b32_e32 v175, 0xffff0000, v83
	v_pk_add_f32 v[168:169], v[84:85], v[168:169]
	v_pk_add_f32 v[170:171], v[86:87], v[170:171]
	v_pk_add_f32 v[172:173], v[88:89], v[172:173]
	v_pk_add_f32 v[174:175], v[90:91], v[174:175]
	v_cvt_pk_bf16_f32 v32, v168, v169
	v_cvt_pk_bf16_f32 v33, v170, v171
	v_cvt_pk_bf16_f32 v34, v172, v173
	v_cvt_pk_bf16_f32 v35, v174, v175
	v_cndmask_b32_e32 v32, 0, v32, vcc
	v_cndmask_b32_e32 v33, 0, v33, vcc
	v_cndmask_b32_e32 v34, 0, v34, vcc
	v_cndmask_b32_e32 v35, 0, v35, vcc
	global_load_dwordx4 v[80:83], v124, s[36:37] offset:128
	global_load_dwordx4 v[84:87], v133, s[66:67] offset:256
	global_load_dwordx4 v[88:91], v133, s[66:67] offset:272
	global_load_dwordx4 v[92:95], v125, s[40:41] offset:128
	global_load_dwordx4 v[96:99], v126, s[40:41] offset:128
	global_load_dwordx4 v[100:103], v127, s[40:41] offset:128
	global_load_dwordx4 v[104:107], v128, s[40:41] offset:128
	global_load_dwordx4 v[108:111], v129, s[40:41] offset:128
	global_load_dwordx4 v[112:115], v130, s[40:41] offset:128
	global_load_dwordx4 v[116:119], v131, s[40:41] offset:128
	global_load_dwordx4 v[120:123], v132, s[40:41] offset:128
	s_waitcnt vmcnt(18)
	v_mfma_f32_16x16x32_bf16 v[4:7], v[32:35], v[136:139], v[4:7]
	s_waitcnt vmcnt(17)
	v_mfma_f32_16x16x32_bf16 v[12:15], v[32:35], v[140:143], v[12:15]
	s_waitcnt vmcnt(16)
	v_mfma_f32_16x16x32_bf16 v[8:11], v[32:35], v[144:147], v[8:11]
	s_waitcnt vmcnt(15)
	v_mfma_f32_16x16x32_bf16 v[20:23], v[32:35], v[148:151], v[20:23]
	s_waitcnt vmcnt(14)
	v_mfma_f32_16x16x32_bf16 v[16:19], v[32:35], v[152:155], v[16:19]
	s_waitcnt vmcnt(13)
	v_mfma_f32_16x16x32_bf16 v[28:31], v[32:35], v[156:159], v[28:31]
	s_waitcnt vmcnt(12)
	v_mfma_f32_16x16x32_bf16 v[24:27], v[32:35], v[160:163], v[24:27]
	s_waitcnt vmcnt(11)
	v_mfma_f32_16x16x32_bf16 v[0:3], v[32:35], v[164:167], v[0:3]
	s_waitcnt vmcnt(8)
	v_lshlrev_b32_e32 v168, 16, v80
	v_and_b32_e32 v169, 0xffff0000, v80
	v_lshlrev_b32_e32 v170, 16, v81
	v_and_b32_e32 v171, 0xffff0000, v81
	v_lshlrev_b32_e32 v172, 16, v82
	v_and_b32_e32 v173, 0xffff0000, v82
	v_lshlrev_b32_e32 v174, 16, v83
	v_and_b32_e32 v175, 0xffff0000, v83
	v_pk_add_f32 v[168:169], v[84:85], v[168:169]
	v_pk_add_f32 v[170:171], v[86:87], v[170:171]
	v_pk_add_f32 v[172:173], v[88:89], v[172:173]
	v_pk_add_f32 v[174:175], v[90:91], v[174:175]
	v_cvt_pk_bf16_f32 v32, v168, v169
	v_cvt_pk_bf16_f32 v33, v170, v171
	v_cvt_pk_bf16_f32 v34, v172, v173
	v_cvt_pk_bf16_f32 v35, v174, v175
	v_cndmask_b32_e32 v32, 0, v32, vcc
	v_cndmask_b32_e32 v33, 0, v33, vcc
	v_cndmask_b32_e32 v34, 0, v34, vcc
	v_cndmask_b32_e32 v35, 0, v35, vcc
	global_load_dwordx4 v[80:83], v124, s[36:37] offset:192
	global_load_dwordx4 v[84:87], v133, s[66:67] offset:384
	global_load_dwordx4 v[88:91], v133, s[66:67] offset:400
	global_load_dwordx4 v[136:139], v125, s[40:41] offset:192
	global_load_dwordx4 v[140:143], v126, s[40:41] offset:192
	global_load_dwordx4 v[144:147], v127, s[40:41] offset:192
	global_load_dwordx4 v[148:151], v128, s[40:41] offset:192
	global_load_dwordx4 v[152:155], v129, s[40:41] offset:192
	global_load_dwordx4 v[156:159], v130, s[40:41] offset:192
	global_load_dwordx4 v[160:163], v131, s[40:41] offset:192
	global_load_dwordx4 v[164:167], v132, s[40:41] offset:192
	s_waitcnt vmcnt(18)
	v_mfma_f32_16x16x32_bf16 v[4:7], v[32:35], v[92:95], v[4:7]
	s_waitcnt vmcnt(17)
	v_mfma_f32_16x16x32_bf16 v[12:15], v[32:35], v[96:99], v[12:15]
	s_waitcnt vmcnt(16)
	v_mfma_f32_16x16x32_bf16 v[8:11], v[32:35], v[100:103], v[8:11]
	s_waitcnt vmcnt(15)
	v_mfma_f32_16x16x32_bf16 v[20:23], v[32:35], v[104:107], v[20:23]
	s_waitcnt vmcnt(14)
	v_mfma_f32_16x16x32_bf16 v[16:19], v[32:35], v[108:111], v[16:19]
	s_waitcnt vmcnt(13)
	v_mfma_f32_16x16x32_bf16 v[28:31], v[32:35], v[112:115], v[28:31]
	s_waitcnt vmcnt(12)
	v_mfma_f32_16x16x32_bf16 v[24:27], v[32:35], v[116:119], v[24:27]
	s_waitcnt vmcnt(11)
	v_mfma_f32_16x16x32_bf16 v[0:3], v[32:35], v[120:123], v[0:3]
	s_waitcnt vmcnt(8)
	v_lshlrev_b32_e32 v168, 16, v80
	v_and_b32_e32 v169, 0xffff0000, v80
	v_lshlrev_b32_e32 v170, 16, v81
	v_and_b32_e32 v171, 0xffff0000, v81
	v_lshlrev_b32_e32 v172, 16, v82
	v_and_b32_e32 v173, 0xffff0000, v82
	v_lshlrev_b32_e32 v174, 16, v83
	v_and_b32_e32 v175, 0xffff0000, v83
	v_pk_add_f32 v[168:169], v[84:85], v[168:169]
	v_pk_add_f32 v[170:171], v[86:87], v[170:171]
	v_pk_add_f32 v[172:173], v[88:89], v[172:173]
	v_pk_add_f32 v[174:175], v[90:91], v[174:175]
	v_cvt_pk_bf16_f32 v32, v168, v169
	v_cvt_pk_bf16_f32 v33, v170, v171
	v_cvt_pk_bf16_f32 v34, v172, v173
	v_cvt_pk_bf16_f32 v35, v174, v175
	v_cndmask_b32_e32 v32, 0, v32, vcc
	v_cndmask_b32_e32 v33, 0, v33, vcc
	v_cndmask_b32_e32 v34, 0, v34, vcc
	v_cndmask_b32_e32 v35, 0, v35, vcc
	s_add_i32 s10, s45, 3
	s_lshl_b32 s11, s10, 8
	s_add_u32 s40, s34, s11
	s_addc_u32 s41, s35, 0
	s_lshl_b32 s11, s10, 9
	s_add_u32 s66, s63, s11
	s_addc_u32 s67, s62, 0
	v_add_u32_e32 v124, s10, v46
	v_mul_u32_u24_e32 v124, s47, v124
	v_lshl_add_u32 v124, v52, 1, v124
	global_load_dwordx4 v[80:83], v124, s[36:37]
	global_load_dwordx4 v[84:87], v133, s[66:67]
	global_load_dwordx4 v[88:91], v133, s[66:67] offset:16
	global_load_dwordx4 v[92:95], v125, s[40:41]
	global_load_dwordx4 v[96:99], v126, s[40:41]
	global_load_dwordx4 v[100:103], v127, s[40:41]
	global_load_dwordx4 v[104:107], v128, s[40:41]
	global_load_dwordx4 v[108:111], v129, s[40:41]
	global_load_dwordx4 v[112:115], v130, s[40:41]
	global_load_dwordx4 v[116:119], v131, s[40:41]
	global_load_dwordx4 v[120:123], v132, s[40:41]
	s_waitcnt vmcnt(18)
; __device__ __forceinline__ float bflo(unsigned u) { return __uint_as_float(u << 16); }
; __device__ __forceinline__ float bfhi(unsigned u) { return __uint_as_float(u & 0xffff0000u); }
; __device__ __forceinline__ void compress_phase(const bf16_t* __restrict__ proj, const float* __restrict__ pos_k, ...
;     ...
;     for (int ks = 0; ks < 16; ++ks) {
;       const int l = w * 4 + (ks >> 2), d0 = (ks & 3) * 32 + quad * 8;
;       bf16x8 a = (bf16x8){0, 0, 0, 0, 0, 0, 0, 0};
;       if (rowvalid) {
;         size_t tokrow = (size_t)b * SEQ + n * 16 + l;
;         uint4 raw = *(const uint4*)(proj + tokrow * NPAD + off + g * 128 + d0);
;         float4 p0 = *(const float4*)(pos + l * 128 + d0), p1 = *(const float4*)(pos + l * 128 + d0 + 4);
;         uint4 pk;
;         pk.x = pack2(bflo(raw.x) + p0.x, bfhi(raw.x) + p0.y);
;         pk.y = pack2(bflo(raw.y) + p0.z, bfhi(raw.y) + p0.w);
;         pk.z = pack2(bflo(raw.z) + p1.x, bfhi(raw.z) + p1.y);
;         pk.w = pack2(bflo(raw.w) + p1.z, bfhi(raw.w) + p1.w);
;         a = *reinterpret_cast<bf16x8*>(&pk);
;       }
; #pragma unroll
;       for (int nt = 0; nt < 8; ++nt) {
;         bf16x8 bw = *(const bf16x8*)(w1t + (size_t)(nt * 16 + c) * 4096 + l * 128 + d0);
;         acc[nt] = __builtin_amdgcn_mfma_f32_16x16x32_bf16(a, bw, acc[nt], 0, 0, 0);
;       }
;     }
	v_mfma_f32_16x16x32_bf16 v[4:7], v[32:35], v[136:139], v[4:7]
	s_waitcnt vmcnt(17)
	v_mfma_f32_16x16x32_bf16 v[12:15], v[32:35], v[140:143], v[12:15]
	s_waitcnt vmcnt(16)
	v_mfma_f32_16x16x32_bf16 v[8:11], v[32:35], v[144:147], v[8:11]
	s_waitcnt vmcnt(15)
	v_mfma_f32_16x16x32_bf16 v[20:23], v[32:35], v[148:151], v[20:23]
	s_waitcnt vmcnt(14)
	v_mfma_f32_16x16x32_bf16 v[16:19], v[32:35], v[152:155], v[16:19]
	s_waitcnt vmcnt(13)
	v_mfma_f32_16x16x32_bf16 v[28:31], v[32:35], v[156:159], v[28:31]
	s_waitcnt vmcnt(12)
	v_mfma_f32_16x16x32_bf16 v[24:27], v[32:35], v[160:163], v[24:27]
	s_waitcnt vmcnt(11)
	v_mfma_f32_16x16x32_bf16 v[0:3], v[32:35], v[164:167], v[0:3]
	s_waitcnt vmcnt(8)
	v_lshlrev_b32_e32 v168, 16, v80
	v_and_b32_e32 v169, 0xffff0000, v80
	v_lshlrev_b32_e32 v170, 16, v81
	v_and_b32_e32 v171, 0xffff0000, v81
	v_lshlrev_b32_e32 v172, 16, v82
	v_and_b32_e32 v173, 0xffff0000, v82
	v_lshlrev_b32_e32 v174, 16, v83
	v_and_b32_e32 v175, 0xffff0000, v83
	v_pk_add_f32 v[168:169], v[84:85], v[168:169]
	v_pk_add_f32 v[170:171], v[86:87], v[170:171]
	v_pk_add_f32 v[172:173], v[88:89], v[172:173]
	v_pk_add_f32 v[174:175], v[90:91], v[174:175]
	v_cvt_pk_bf16_f32 v32, v168, v169
	v_cvt_pk_bf16_f32 v33, v170, v171
	v_cvt_pk_bf16_f32 v34, v172, v173
	v_cvt_pk_bf16_f32 v35, v174, v175
	v_cndmask_b32_e32 v32, 0, v32, vcc
	v_cndmask_b32_e32 v33, 0, v33, vcc
	v_cndmask_b32_e32 v34, 0, v34, vcc
	v_cndmask_b32_e32 v35, 0, v35, vcc
	global_load_dwordx4 v[80:83], v124, s[36:37] offset:64
	global_load_dwordx4 v[84:87], v133, s[66:67] offset:128
	global_load_dwordx4 v[88:91], v133, s[66:67] offset:144
	global_load_dwordx4 v[136:139], v125, s[40:41] offset:64
	global_load_dwordx4 v[140:143], v126, s[40:41] offset:64
	global_load_dwordx4 v[144:147], v127, s[40:41] offset:64
	global_load_dwordx4 v[148:151], v128, s[40:41] offset:64
	global_load_dwordx4 v[152:155], v129, s[40:41] offset:64
	global_load_dwordx4 v[156:159], v130, s[40:41] offset:64
	global_load_dwordx4 v[160:163], v131, s[40:41] offset:64
	global_load_dwordx4 v[164:167], v132, s[40:41] offset:64
	s_waitcnt vmcnt(18)
	v_mfma_f32_16x16x32_bf16 v[4:7], v[32:35], v[92:95], v[4:7]
	s_waitcnt vmcnt(17)
	v_mfma_f32_16x16x32_bf16 v[12:15], v[32:35], v[96:99], v[12:15]
	s_waitcnt vmcnt(16)
	v_mfma_f32_16x16x32_bf16 v[8:11], v[32:35], v[100:103], v[8:11]
	s_waitcnt vmcnt(15)
	v_mfma_f32_16x16x32_bf16 v[20:23], v[32:35], v[104:107], v[20:23]
	s_waitcnt vmcnt(14)
	v_mfma_f32_16x16x32_bf16 v[16:19], v[32:35], v[108:111], v[16:19]
	s_waitcnt vmcnt(13)
	v_mfma_f32_16x16x32_bf16 v[28:31], v[32:35], v[112:115], v[28:31]
	s_waitcnt vmcnt(12)
	v_mfma_f32_16x16x32_bf16 v[24:27], v[32:35], v[116:119], v[24:27]
	s_waitcnt vmcnt(11)
	v_mfma_f32_16x16x32_bf16 v[0:3], v[32:35], v[120:123], v[0:3]
	s_waitcnt vmcnt(8)
	v_lshlrev_b32_e32 v168, 16, v80
	v_and_b32_e32 v169, 0xffff0000, v80
	v_lshlrev_b32_e32 v170, 16, v81
	v_and_b32_e32 v171, 0xffff0000, v81
	v_lshlrev_b32_e32 v172, 16, v82
	v_and_b32_e32 v173, 0xffff0000, v82
	v_lshlrev_b32_e32 v174, 16, v83
	v_and_b32_e32 v175, 0xffff0000, v83
	v_pk_add_f32 v[168:169], v[84:85], v[168:169]
	v_pk_add_f32 v[170:171], v[86:87], v[170:171]
	v_pk_add_f32 v[172:173], v[88:89], v[172:173]
	v_pk_add_f32 v[174:175], v[90:91], v[174:175]
	v_cvt_pk_bf16_f32 v32, v168, v169
	v_cvt_pk_bf16_f32 v33, v170, v171
	v_cvt_pk_bf16_f32 v34, v172, v173
	v_cvt_pk_bf16_f32 v35, v174, v175
	v_cndmask_b32_e32 v32, 0, v32, vcc
	v_cndmask_b32_e32 v33, 0, v33, vcc
	v_cndmask_b32_e32 v34, 0, v34, vcc
	v_cndmask_b32_e32 v35, 0, v35, vcc
	global_load_dwordx4 v[80:83], v124, s[36:37] offset:128
	global_load_dwordx4 v[84:87], v133, s[66:67] offset:256
	global_load_dwordx4 v[88:91], v133, s[66:67] offset:272
	global_load_dwordx4 v[92:95], v125, s[40:41] offset:128
	global_load_dwordx4 v[96:99], v126, s[40:41] offset:128
	global_load_dwordx4 v[100:103], v127, s[40:41] offset:128
	global_load_dwordx4 v[104:107], v128, s[40:41] offset:128
	global_load_dwordx4 v[108:111], v129, s[40:41] offset:128
	global_load_dwordx4 v[112:115], v130, s[40:41] offset:128
	global_load_dwordx4 v[116:119], v131, s[40:41] offset:128
	global_load_dwordx4 v[120:123], v132, s[40:41] offset:128
	s_waitcnt vmcnt(18)
; __device__ __forceinline__ float bflo(unsigned u) { return __uint_as_float(u << 16); }
; __device__ __forceinline__ float bfhi(unsigned u) { return __uint_as_float(u & 0xffff0000u); }
; __device__ __forceinline__ void compress_phase(const bf16_t* __restrict__ proj, const float* __restrict__ pos_k, ...
;     ...
;     for (int ks = 0; ks < 16; ++ks) {
;       const int l = w * 4 + (ks >> 2), d0 = (ks & 3) * 32 + quad * 8;
;       bf16x8 a = (bf16x8){0, 0, 0, 0, 0, 0, 0, 0};
;       if (rowvalid) {
;         size_t tokrow = (size_t)b * SEQ + n * 16 + l;
;         uint4 raw = *(const uint4*)(proj + tokrow * NPAD + off + g * 128 + d0);
;         float4 p0 = *(const float4*)(pos + l * 128 + d0), p1 = *(const float4*)(pos + l * 128 + d0 + 4);
;         uint4 pk;
;         pk.x = pack2(bflo(raw.x) + p0.x, bfhi(raw.x) + p0.y);
;         pk.y = pack2(bflo(raw.y) + p0.z, bfhi(raw.y) + p0.w);
;         pk.z = pack2(bflo(raw.z) + p1.x, bfhi(raw.z) + p1.y);
;         pk.w = pack2(bflo(raw.w) + p1.z, bfhi(raw.w) + p1.w);
;         a = *reinterpret_cast<bf16x8*>(&pk);
;       }
; #pragma unroll
;       for (int nt = 0; nt < 8; ++nt) {
;         bf16x8 bw = *(const bf16x8*)(w1t + (size_t)(nt * 16 + c) * 4096 + l * 128 + d0);
;         acc[nt] = __builtin_amdgcn_mfma_f32_16x16x32_bf16(a, bw, acc[nt], 0, 0, 0);
;       }
;     }
	v_mfma_f32_16x16x32_bf16 v[4:7], v[32:35], v[136:139], v[4:7]
	s_waitcnt vmcnt(17)
	v_mfma_f32_16x16x32_bf16 v[12:15], v[32:35], v[140:143], v[12:15]
	s_waitcnt vmcnt(16)
	v_mfma_f32_16x16x32_bf16 v[8:11], v[32:35], v[144:147], v[8:11]
	s_waitcnt vmcnt(15)
	v_mfma_f32_16x16x32_bf16 v[20:23], v[32:35], v[148:151], v[20:23]
	s_waitcnt vmcnt(14)
	v_mfma_f32_16x16x32_bf16 v[16:19], v[32:35], v[152:155], v[16:19]
	s_waitcnt vmcnt(13)
	v_mfma_f32_16x16x32_bf16 v[28:31], v[32:35], v[156:159], v[28:31]
	s_waitcnt vmcnt(12)
	v_mfma_f32_16x16x32_bf16 v[24:27], v[32:35], v[160:163], v[24:27]
	s_waitcnt vmcnt(11)
	v_mfma_f32_16x16x32_bf16 v[0:3], v[32:35], v[164:167], v[0:3]
	s_waitcnt vmcnt(8)
	v_lshlrev_b32_e32 v168, 16, v80
	v_and_b32_e32 v169, 0xffff0000, v80
	v_lshlrev_b32_e32 v170, 16, v81
	v_and_b32_e32 v171, 0xffff0000, v81
	v_lshlrev_b32_e32 v172, 16, v82
	v_and_b32_e32 v173, 0xffff0000, v82
	v_lshlrev_b32_e32 v174, 16, v83
	v_and_b32_e32 v175, 0xffff0000, v83
	v_pk_add_f32 v[168:169], v[84:85], v[168:169]
	v_pk_add_f32 v[170:171], v[86:87], v[170:171]
	v_pk_add_f32 v[172:173], v[88:89], v[172:173]
	v_pk_add_f32 v[174:175], v[90:91], v[174:175]
	v_cvt_pk_bf16_f32 v32, v168, v169
	v_cvt_pk_bf16_f32 v33, v170, v171
	v_cvt_pk_bf16_f32 v34, v172, v173
	v_cvt_pk_bf16_f32 v35, v174, v175
	v_cndmask_b32_e32 v32, 0, v32, vcc
	v_cndmask_b32_e32 v33, 0, v33, vcc
	v_cndmask_b32_e32 v34, 0, v34, vcc
	v_cndmask_b32_e32 v35, 0, v35, vcc
	global_load_dwordx4 v[80:83], v124, s[36:37] offset:192
	global_load_dwordx4 v[84:87], v133, s[66:67] offset:384
	global_load_dwordx4 v[88:91], v133, s[66:67] offset:400
	global_load_dwordx4 v[136:139], v125, s[40:41] offset:192
	global_load_dwordx4 v[140:143], v126, s[40:41] offset:192
	global_load_dwordx4 v[144:147], v127, s[40:41] offset:192
	global_load_dwordx4 v[148:151], v128, s[40:41] offset:192
	global_load_dwordx4 v[152:155], v129, s[40:41] offset:192
	global_load_dwordx4 v[156:159], v130, s[40:41] offset:192
	global_load_dwordx4 v[160:163], v131, s[40:41] offset:192
	global_load_dwordx4 v[164:167], v132, s[40:41] offset:192
	s_waitcnt vmcnt(18)
	v_mfma_f32_16x16x32_bf16 v[4:7], v[32:35], v[92:95], v[4:7]
	s_waitcnt vmcnt(17)
	v_mfma_f32_16x16x32_bf16 v[12:15], v[32:35], v[96:99], v[12:15]
	s_waitcnt vmcnt(16)
	v_mfma_f32_16x16x32_bf16 v[8:11], v[32:35], v[100:103], v[8:11]
	s_waitcnt vmcnt(15)
	v_mfma_f32_16x16x32_bf16 v[20:23], v[32:35], v[104:107], v[20:23]
	s_waitcnt vmcnt(14)
	v_mfma_f32_16x16x32_bf16 v[16:19], v[32:35], v[108:111], v[16:19]
	s_waitcnt vmcnt(13)
	v_mfma_f32_16x16x32_bf16 v[28:31], v[32:35], v[112:115], v[28:31]
	s_waitcnt vmcnt(12)
	v_mfma_f32_16x16x32_bf16 v[24:27], v[32:35], v[116:119], v[24:27]
	s_waitcnt vmcnt(11)
	v_mfma_f32_16x16x32_bf16 v[0:3], v[32:35], v[120:123], v[0:3]
	s_waitcnt vmcnt(8)
	v_lshlrev_b32_e32 v168, 16, v80
	v_and_b32_e32 v169, 0xffff0000, v80
	v_lshlrev_b32_e32 v170, 16, v81
	v_and_b32_e32 v171, 0xffff0000, v81
	v_lshlrev_b32_e32 v172, 16, v82
	v_and_b32_e32 v173, 0xffff0000, v82
	v_lshlrev_b32_e32 v174, 16, v83
	v_and_b32_e32 v175, 0xffff0000, v83
	v_pk_add_f32 v[168:169], v[84:85], v[168:169]
	v_pk_add_f32 v[170:171], v[86:87], v[170:171]
	v_pk_add_f32 v[172:173], v[88:89], v[172:173]
	v_pk_add_f32 v[174:175], v[90:91], v[174:175]
	v_cvt_pk_bf16_f32 v32, v168, v169
	v_cvt_pk_bf16_f32 v33, v170, v171
	v_cvt_pk_bf16_f32 v34, v172, v173
	v_cvt_pk_bf16_f32 v35, v174, v175
	v_cndmask_b32_e32 v32, 0, v32, vcc
	v_cndmask_b32_e32 v33, 0, v33, vcc
	v_cndmask_b32_e32 v34, 0, v34, vcc
	v_cndmask_b32_e32 v35, 0, v35, vcc
	s_nop 1
	s_waitcnt vmcnt(7)
	v_mfma_f32_16x16x32_bf16 v[4:7], v[32:35], v[136:139], v[4:7]
	s_waitcnt vmcnt(6)
	v_mfma_f32_16x16x32_bf16 v[12:15], v[32:35], v[140:143], v[12:15]
	s_waitcnt vmcnt(5)
	v_mfma_f32_16x16x32_bf16 v[8:11], v[32:35], v[144:147], v[8:11]
	s_waitcnt vmcnt(4)
	v_mfma_f32_16x16x32_bf16 v[20:23], v[32:35], v[148:151], v[20:23]
	s_waitcnt vmcnt(3)
	v_mfma_f32_16x16x32_bf16 v[16:19], v[32:35], v[152:155], v[16:19]
	s_waitcnt vmcnt(2)
	v_mfma_f32_16x16x32_bf16 v[28:31], v[32:35], v[156:159], v[28:31]
	s_waitcnt vmcnt(1)
	v_mfma_f32_16x16x32_bf16 v[24:27], v[32:35], v[160:163], v[24:27]
	s_waitcnt vmcnt(0)
	v_mfma_f32_16x16x32_bf16 v[0:3], v[32:35], v[164:167], v[0:3]
	s_nop 7
	s_branch .LBB0_210

;     ...
;   const int ntn = Npad / 256, ntk = K / 64;
;   const int total = (it_end < 0) ? ntn * ntk : it_end;
;   if (bid < 0) { bid = blockIdx.x; nb = gridDim.x; }
;   const int tid = opaque_tid();
;   for (int it = it_begin + bid; it < total; it += nb) {
;     const int tn = it % ntn, tk = it / ntn;
;     const int k0 = tk * 64, n0 = tn * 256;
;     f32x4 v[8];
; #pragma unroll
;     for (int i = 0; i < 8; ++i) {
;       const int id = tid + i * 512;
;       const int r = id >> 6, c4 = (id & 63) * 4;
;       v[i] = (f32x4){0.f, 0.f, 0.f, 0.f};
;       if (n0 + c4 < N) v[i] = __builtin_nontemporal_load((const f32x4*)(src + (size_t)(k0 + r) * N + n0 + c4));
;     }
;     __syncthreads();
; #pragma unroll
;     for (int i = 0; i < 8; ++i) {
;       const int id = tid + i * 512;
;       const int r = id >> 6, c4 = (id & 63) * 4;
;       tile[r * 257 + c4 + 0] = v[i][0];
;       tile[r * 257 + c4 + 1] = v[i][1];
;       tile[r * 257 + c4 + 2] = v[i][2];
;       tile[r * 257 + c4 + 3] = v[i][3];
;     }
;     __syncthreads();
; #pragma unroll
;     for (int i = 0; i < 4; ++i) {
;       const int id = tid + i * 512;
;       const int n = id >> 3, kc = id & 7;
;       uint4 o;
;       o.x = pack2(tile[(kc * 8 + 0) * 257 + n], tile[(kc * 8 + 1) * 257 + n]);
;       o.y = pack2(tile[(kc * 8 + 2) * 257 + n], tile[(kc * 8 + 3) * 257 + n]);
;       o.z = pack2(tile[(kc * 8 + 4) * 257 + n], tile[(kc * 8 + 5) * 257 + n]);
;       o.w = pack2(tile[(kc * 8 + 6) * 257 + n], tile[(kc * 8 + 7) * 257 + n]);
;       *(uint4*)(dst + (size_t)(n0 + n) * K + k0 + kc * 8) = o;
;     }
.LBB0_493:
	s_movk_i32 s44, 0x7a0
.Lwo_mod:
	s_cmp_ge_u32 s44, s18
	s_cbranch_scc0 .Lwo_moddone
	s_sub_i32 s44, s44, s18
	s_branch .Lwo_mod
.Lwo_moddone:
	s_cmp_eq_u32 s44, 0
	s_cbranch_scc1 .Lwo_done
	s_cmp_lt_u32 s2, s44
	s_cbranch_scc1 .Lwo_done
	s_sub_i32 s98, s2, s44
	s_sub_i32 s99, s18, s44
	s_cmpk_gt_i32 s98, 0x3ff
	s_cbranch_scc1 .Lwo_done
	s_lshl_b32 s100, s99, 8
	s_mov_b32 s12, 1
	s_mov_b32 s13, 0
	s_movk_i32 s59, 0x404
	s_mov_b64 s[42:43], 0xf400000
	s_movk_i32 s60, 0x1000
	v_mov_b32_e32 v35, 0
	s_mov_b64 s[44:45], s[0:1]
	v_mov_b32_e32 v2, v254
	s_load_dwordx2 s[46:47], s[44:45], 0x68
	s_nop 0
	s_load_dwordx2 s[44:45], s[44:45], 0x48
	s_lshl_b64 s[48:49], s[12:13], 25
	v_lshlrev_b32_e32 v1, 2, v2
	v_and_b32_e32 v1, 0xfc, v1
	s_waitcnt lgkmcnt(0)
	s_add_u32 s46, s46, s48
	s_addc_u32 s47, s47, s49
	s_lshl_b64 s[48:49], s[12:13], 26
	s_add_u32 s44, s44, s48
	v_lshlrev_b32_e32 v4, 3, v2
	s_addc_u32 s45, s45, s49
	v_lshlrev_b32_e32 v34, 2, v1
	v_and_b32_e32 v4, 56, v4
	v_lshl_add_u64 v[36:37], s[44:45], 0, v[34:35]
	v_add_u32_e32 v3, 16, v34
	v_lshlrev_b32_e32 v34, 1, v4
	v_add_u32_e32 v8, 0x800, v2
	v_mad_u32_u24 v6, v4, s59, 16
	v_lshl_add_u64 v[4:5], s[46:47], 0, v[34:35]
	v_ashrrev_i32_e32 v47, 6, v8
	v_add_u32_e32 v8, 0xa00, v2
	v_lshl_add_u64 v[38:39], v[4:5], 0, s[42:43]
	v_ashrrev_i32_e32 v34, 3, v2
	v_ashrrev_i32_e32 v43, 6, v2
	v_add_u32_e32 v4, 0x200, v2
	v_add_u32_e32 v5, 0x400, v2
	v_add_u32_e32 v7, 0x600, v2
	v_ashrrev_i32_e32 v48, 6, v8
	v_add_u32_e32 v8, 0xc00, v2
	v_add_u32_e32 v2, 0xe00, v2
	v_ashrrev_i32_e32 v44, 6, v4
	v_ashrrev_i32_e32 v45, 6, v5
	v_ashrrev_i32_e32 v46, 6, v7
	v_ashrrev_i32_e32 v49, 6, v8
	v_ashrrev_i32_e32 v50, 6, v2
	v_mul_lo_u32 v2, v43, s59
	v_mul_lo_u32 v8, v44, s59
	v_mul_lo_u32 v9, v45, s59
	v_mul_lo_u32 v10, v46, s59
	v_mul_lo_u32 v11, v47, s59
	v_mul_lo_u32 v12, v48, s59
	v_mul_lo_u32 v13, v49, s59
	v_ashrrev_i32_e32 v51, 3, v4
	v_ashrrev_i32_e32 v53, 3, v5
	v_ashrrev_i32_e32 v55, 3, v7
	v_mul_lo_u32 v4, v50, s59
	v_lshl_add_u32 v42, v34, 2, v6
	v_lshl_add_u32 v52, v51, 2, v6
	v_lshl_add_u32 v54, v53, 2, v6
	v_lshl_add_u32 v56, v55, 2, v6
	v_add_u32_e32 v57, v3, v2
	v_add_u32_e32 v58, v3, v8
	v_add_u32_e32 v59, v3, v9
	v_add_u32_e32 v60, v3, v10
	v_add_u32_e32 v61, v3, v11
	v_add_u32_e32 v62, v3, v12
	v_add_u32_e32 v63, v3, v13
	v_add_u32_e32 v64, v3, v4
	s_lshl_b32 s48, s98, 8
	s_mov_b32 s49, s98
	s_branch .Lwo_30
.Lwo_29:
	s_or_b64 exec, exec, s[46:47]
	s_barrier
	s_waitcnt vmcnt(0)
	ds_write2_b32 v57, v6, v7 offset1:1
	ds_write2_b32 v57, v8, v9 offset0:2 offset1:3
	ds_write2_b32 v58, v2, v3 offset1:1
	ds_write2_b32 v58, v4, v5 offset0:2 offset1:3
	ds_write2_b32 v59, v14, v15 offset1:1
	ds_write2_b32 v59, v16, v17 offset0:2 offset1:3
	ds_write2_b32 v60, v10, v11 offset1:1
	ds_write2_b32 v60, v12, v13 offset0:2 offset1:3
	ds_write2_b32 v61, v22, v23 offset1:1
	ds_write2_b32 v61, v24, v25 offset0:2 offset1:3
	ds_write2_b32 v62, v18, v19 offset1:1
	ds_write2_b32 v62, v20, v21 offset0:2 offset1:3
	ds_write2_b32 v63, v30, v31 offset1:1
	ds_write2_b32 v63, v32, v33 offset0:2 offset1:3
	ds_write2_b32 v64, v26, v27 offset1:1
	ds_write2_b32 v64, v28, v29 offset0:2 offset1:3
	s_waitcnt lgkmcnt(0)
	s_barrier
	ds_read_b32 v2, v42
	ds_read_b32 v3, v42 offset:1028
	ds_read_b32 v4, v42 offset:2056
	ds_read_b32 v5, v42 offset:3084
	ds_read_b32 v8, v42 offset:4112
	ds_read_b32 v9, v42 offset:5140
	ds_read_b32 v10, v42 offset:6168
	ds_read_b32 v11, v42 offset:7196
	s_sub_i32 s46, 0, s45
	s_add_i32 s46, s46, s48
	s_waitcnt lgkmcnt(6)
	v_cvt_pk_bf16_f32 v2, v2, v3
	s_waitcnt lgkmcnt(4)
	v_cvt_pk_bf16_f32 v3, v4, v5
	s_waitcnt lgkmcnt(2)
	v_cvt_pk_bf16_f32 v4, v8, v9
	s_waitcnt lgkmcnt(0)
	v_cvt_pk_bf16_f32 v5, v10, v11
	v_add_u32_e32 v8, s46, v34
	ds_read_b32 v10, v52
	ds_read_b32 v11, v52 offset:1028
	ds_read_b32 v12, v52 offset:2056
	ds_read_b32 v13, v52 offset:3084
	ds_read_b32 v14, v52 offset:4112
	ds_read_b32 v15, v52 offset:5140
	ds_read_b32 v16, v52 offset:6168
	ds_read_b32 v17, v52 offset:7196
	s_ashr_i32 s45, s44, 31
	v_ashrrev_i32_e32 v9, 31, v8
	v_lshl_add_u64 v[6:7], s[44:45], 1, v[38:39]
	v_lshlrev_b64 v[8:9], 13, v[8:9]
	v_lshl_add_u64 v[8:9], v[6:7], 0, v[8:9]
	global_store_dwordx4 v[8:9], v[2:5], off
	v_add_u32_e32 v8, s46, v51
	v_ashrrev_i32_e32 v9, 31, v8
	s_waitcnt lgkmcnt(6)
	v_cvt_pk_bf16_f32 v2, v10, v11
	s_waitcnt lgkmcnt(4)
	v_cvt_pk_bf16_f32 v3, v12, v13
	s_waitcnt lgkmcnt(2)
	v_cvt_pk_bf16_f32 v4, v14, v15
	s_waitcnt lgkmcnt(0)
	v_cvt_pk_bf16_f32 v5, v16, v17
	ds_read_b32 v10, v54
	ds_read_b32 v11, v54 offset:1028
	ds_read_b32 v12, v54 offset:2056
	ds_read_b32 v13, v54 offset:3084
	ds_read_b32 v14, v54 offset:4112
	ds_read_b32 v15, v54 offset:5140
	ds_read_b32 v16, v54 offset:6168
	ds_read_b32 v17, v54 offset:7196
	v_lshlrev_b64 v[8:9], 13, v[8:9]
	v_lshl_add_u64 v[8:9], v[6:7], 0, v[8:9]
	global_store_dwordx4 v[8:9], v[2:5], off
	v_add_u32_e32 v8, s46, v53
	v_ashrrev_i32_e32 v9, 31, v8
	s_waitcnt lgkmcnt(6)
	v_cvt_pk_bf16_f32 v2, v10, v11
	s_waitcnt lgkmcnt(4)
	v_cvt_pk_bf16_f32 v3, v12, v13
	s_waitcnt lgkmcnt(2)
	v_cvt_pk_bf16_f32 v4, v14, v15
	s_waitcnt lgkmcnt(0)
	v_cvt_pk_bf16_f32 v5, v16, v17
	v_lshlrev_b64 v[8:9], 13, v[8:9]
	ds_read_b32 v10, v56
	ds_read_b32 v11, v56 offset:1028
	ds_read_b32 v12, v56 offset:2056
	ds_read_b32 v13, v56 offset:3084
	ds_read_b32 v14, v56 offset:4112
	ds_read_b32 v15, v56 offset:5140
	ds_read_b32 v16, v56 offset:6168
	ds_read_b32 v17, v56 offset:7196
	v_lshl_add_u64 v[8:9], v[6:7], 0, v[8:9]
	global_store_dwordx4 v[8:9], v[2:5], off
	v_add_u32_e32 v8, s46, v55
	v_ashrrev_i32_e32 v9, 31, v8
	v_lshlrev_b64 v[8:9], 13, v[8:9]
	s_add_i32 s49, s49, s99
	s_add_i32 s48, s48, s100
	s_waitcnt lgkmcnt(6)
	v_cvt_pk_bf16_f32 v2, v10, v11
	s_waitcnt lgkmcnt(4)
	v_cvt_pk_bf16_f32 v3, v12, v13
	s_waitcnt lgkmcnt(2)
	v_cvt_pk_bf16_f32 v4, v14, v15
	s_waitcnt lgkmcnt(0)
	v_cvt_pk_bf16_f32 v5, v16, v17
	v_lshl_add_u64 v[6:7], v[6:7], 0, v[8:9]
	s_cmpk_lt_i32 s49, 0x400
	global_store_dwordx4 v[6:7], v[2:5], off
	s_cbranch_scc0 .Lwo_done

; __device__ __forceinline__ unsigned xb_add(unsigned* p, unsigned v) { return __hip_atomic_fetch_add(p, v, __ATOMIC_RELAXED, __HIP_MEMORY_SCOPE_AGENT); }
;     ...
;   for (int it = it_begin + bid; it < total; it += nb) {
;     const int tn = it % ntn, tk = it / ntn;
;     const int k0 = tk * 64, n0 = tn * 256;
;     f32x4 v[8];
; #pragma unroll
;     for (int i = 0; i < 8; ++i) {
;       const int id = tid + i * 512;
;       const int r = id >> 6, c4 = (id & 63) * 4;
;       v[i] = (f32x4){0.f, 0.f, 0.f, 0.f};
;       if (n0 + c4 < N) v[i] = __builtin_nontemporal_load((const f32x4*)(src + (size_t)(k0 + r) * N + n0 + c4));
;     }
; __device__ __forceinline__ void xcd_barrier(const XcdBarrier& b) {
;   asm volatile("s_waitcnt vmcnt(0)" ::: "memory");
;   __syncthreads();
;   if (threadIdx.x == 0) {
;     unsigned* bar = b.bar;
;     __builtin_amdgcn_s_waitcnt(0);
;     const unsigned old = xb_add(&bar[XB_XSUB(b.x)], 1u);
.Lwo_44:
	s_or_b64 exec, exec, s[46:47]
	v_mov_b32_e32 v27, 0
	v_mov_b32_e32 v28, 0
	v_mov_b32_e32 v29, 0
	s_and_saveexec_b64 s[46:47], vcc
	s_cbranch_execz .Lwo_29
	v_add_u32_e32 v26, s44, v50
	v_ashrrev_i32_e32 v27, 31, v26
	v_lshlrev_b64 v[26:27], 14, v[26:27]
	v_lshl_add_u64 v[26:27], v[40:41], 0, v[26:27]
	global_load_dwordx4 v[26:29], v[26:27], off nt
	s_branch .Lwo_29
.Lwo_done:
	s_waitcnt vmcnt(0)
	s_waitcnt vmcnt(0)
	s_barrier
	s_and_saveexec_b64 s[10:11], s[4:5]
	s_cbranch_execz .LBB0_530
	s_mov_b64 s[12:13], exec
	v_mbcnt_lo_u32_b32 v0, s12, 0
	v_mbcnt_hi_u32_b32 v0, s13, v0
	s_lshl_b32 s8, s84, 6
	s_mov_b32 s17, 0
	v_cmp_eq_u32_e32 vcc, 0, v0
	s_waitcnt vmcnt(0) expcnt(0) lgkmcnt(0)
	s_and_saveexec_b64 s[14:15], vcc
	s_cbranch_execz .LBB0_496
	s_add_i32 s16, s8, 0x500
	s_lshl_b64 s[16:17], s[16:17], 2
	s_add_u32 s16, s20, s16
	s_addc_u32 s17, s21, s17
	s_bcnt1_i32_b64 s9, s[12:13]
	v_mov_b32_e32 v1, 0
	v_mov_b32_e32 v2, s9
	global_atomic_add v1, v1, v2, s[16:17] sc0

; __device__ __forceinline__ float bflo(unsigned u) { return __uint_as_float(u << 16); }
; __device__ __forceinline__ float bfhi(unsigned u) { return __uint_as_float(u & 0xffff0000u); }
; __device__ __forceinline__ void compress_phase(const bf16_t* __restrict__ proj, const float* __restrict__ pos_k, ...
;     ...
;   for (int it = blockIdx.x; it < 256; it += gridDim.x) {
;     const int kv = it >> 7, b = (it >> 6) & 1, g = (it >> 4) & 3, ntile = it & 15;
;     const float* pos = kv ? pos_v : pos_k;
;     const int off = kv ? OFF_VC : OFF_KC;
;     const bf16_t* w1t = W1T + (size_t)kv * 128 * 4096;
;     const bf16_t* w2t = W2T + (size_t)kv * 128 * 128;
;     const int n0 = ntile * 16;
;     const int n = n0 + c;
;     const bool rowvalid = n < 255;
;     f32x4 acc[8];
; #pragma unroll
;     for (int i = 0; i < 8; ++i) acc[i] = (f32x4){0.f, 0.f, 0.f, 0.f};
;     for (int ks = 0; ks < 16; ++ks) {
;       const int l = w * 4 + (ks >> 2), d0 = (ks & 3) * 32 + quad * 8;
;       bf16x8 a = (bf16x8){0, 0, 0, 0, 0, 0, 0, 0};
;       if (rowvalid) {
;         size_t tokrow = (size_t)b * SEQ + n * 16 + l;
;         uint4 raw = *(const uint4*)(proj + tokrow * NPAD + off + g * 128 + d0);
;         float4 p0 = *(const float4*)(pos + l * 128 + d0), p1 = *(const float4*)(pos + l * 128 + d0 + 4);
;         uint4 pk;
;         pk.x = pack2(bflo(raw.x) + p0.x, bfhi(raw.x) + p0.y);
;         pk.y = pack2(bflo(raw.y) + p0.z, bfhi(raw.y) + p0.w);
;         pk.z = pack2(bflo(raw.z) + p1.x, bfhi(raw.z) + p1.y);
;         pk.w = pack2(bflo(raw.w) + p1.z, bfhi(raw.w) + p1.w);
;         a = *reinterpret_cast<bf16x8*>(&pk);
;       }
; #pragma unroll
;       for (int nt = 0; nt < 8; ++nt) {
;         bf16x8 bw = *(const bf16x8*)(w1t + (size_t)(nt * 16 + c) * 4096 + l * 128 + d0);
;         acc[nt] = __builtin_amdgcn_mfma_f32_16x16x32_bf16(a, bw, acc[nt], 0, 0, 0);
;       }
;     }
.LBB0_547:
	s_ashr_i32 s26, s51, 7
	s_lshr_b32 s52, s51, 6
	s_cmpk_lt_u32 s51, 0x80
	s_cselect_b64 s[6:7], -1, 0
	s_and_b64 s[10:11], s[6:7], exec
	s_cselect_b32 s11, s12, s14
	s_cselect_b32 s10, s13, s15
	s_cselect_b32 s30, s39, 0x5400
	s_add_u32 s56, s11, 0x4000
	s_addc_u32 s57, s10, 0
	s_ashr_i32 s27, s26, 31
	s_lshl_b64 s[10:11], s[26:27], 20
	s_add_u32 s28, s9, s10
	s_addc_u32 s29, s19, s11
	s_lshl_b32 s10, s51, 4
	s_and_b32 s24, s10, 0xf0
	s_bfe_u32 s53, s51, 0x10006
	s_bfe_u32 s10, s51, 0x20004
	s_add_u32 s11, s3, s30
	v_or_b32_e32 v0, s24, v49
	s_addc_u32 s31, s8, 0
	s_lshl_b32 s30, s53, 12
	s_lshl_b32 s55, s10, 7
	s_lshl_b32 s54, s10, 8
	v_lshl_or_b32 v46, v0, 4, s30
	s_add_u32 s30, s11, s54
	v_cmp_ne_u32_e32 vcc, s40, v0
	v_mov_b32_e32 v47, v37
	s_addc_u32 s31, s31, 0
	s_mov_b32 s58, 0
	s_mov_b32 s59, 0
	v_mov_b32_e32 v0, v37
	v_mov_b32_e32 v1, v37
	v_mov_b32_e32 v2, v37
	v_mov_b32_e32 v3, v37
	v_mov_b32_e32 v4, v37
	v_mov_b32_e32 v5, v37
	v_mov_b32_e32 v6, v37
	v_mov_b32_e32 v7, v37
	v_mov_b32_e32 v12, v37
	v_mov_b32_e32 v13, v37
	v_mov_b32_e32 v14, v37
	v_mov_b32_e32 v15, v37
	v_mov_b32_e32 v8, v37
	v_mov_b32_e32 v9, v37
	v_mov_b32_e32 v10, v37
	v_mov_b32_e32 v11, v37
	v_mov_b32_e32 v20, v37
	v_mov_b32_e32 v21, v37
	v_mov_b32_e32 v22, v37
	v_mov_b32_e32 v23, v37
	v_mov_b32_e32 v16, v37
	v_mov_b32_e32 v17, v37
	v_mov_b32_e32 v18, v37
	v_mov_b32_e32 v19, v37
	v_mov_b32_e32 v28, v37
	v_mov_b32_e32 v29, v37
	v_mov_b32_e32 v30, v37
	v_mov_b32_e32 v31, v37
	v_mov_b32_e32 v24, v37
	v_mov_b32_e32 v25, v37
	v_mov_b32_e32 v26, v37
	v_mov_b32_e32 v27, v37
	v_lshl_add_u32 v125, v52, 1, v44
	v_add_u32_e32 v126, 0x20000, v125
	v_add_u32_e32 v127, 0x40000, v125
	v_add_u32_e32 v128, 0x60000, v125
	v_add_u32_e32 v129, 0x80000, v125
	v_add_u32_e32 v130, 0xa0000, v125
	v_add_u32_e32 v131, 0xc0000, v125
	v_add_u32_e32 v132, 0xe0000, v125
	v_lshlrev_b32_e32 v133, 2, v52
	s_add_i32 s10, s38, 0
	s_lshl_b32 s11, s10, 8
	s_add_u32 s34, s28, s11
	s_addc_u32 s35, s29, 0
	s_lshl_b32 s11, s10, 9
	s_add_u32 s60, s56, s11
	s_addc_u32 s61, s57, 0
	v_add_u32_e32 v124, s10, v46
	v_mul_u32_u24_e32 v124, s41, v124
	v_lshl_add_u32 v124, v52, 1, v124
	global_load_dwordx4 v[80:83], v124, s[30:31]
	global_load_dwordx4 v[84:87], v133, s[60:61]
	global_load_dwordx4 v[88:91], v133, s[60:61] offset:16
	global_load_dwordx4 v[92:95], v125, s[34:35]
	global_load_dwordx4 v[96:99], v126, s[34:35]
	global_load_dwordx4 v[100:103], v127, s[34:35]
	global_load_dwordx4 v[104:107], v128, s[34:35]
	global_load_dwordx4 v[108:111], v129, s[34:35]
	global_load_dwordx4 v[112:115], v130, s[34:35]
	global_load_dwordx4 v[116:119], v131, s[34:35]
	global_load_dwordx4 v[120:123], v132, s[34:35]
	s_waitcnt vmcnt(8)
	v_lshlrev_b32_e32 v168, 16, v80
	v_and_b32_e32 v169, 0xffff0000, v80
	v_lshlrev_b32_e32 v170, 16, v81
	v_and_b32_e32 v171, 0xffff0000, v81
	v_lshlrev_b32_e32 v172, 16, v82
	v_and_b32_e32 v173, 0xffff0000, v82
	v_lshlrev_b32_e32 v174, 16, v83
	v_and_b32_e32 v175, 0xffff0000, v83
	v_pk_add_f32 v[168:169], v[84:85], v[168:169]
	v_pk_add_f32 v[170:171], v[86:87], v[170:171]
	v_pk_add_f32 v[172:173], v[88:89], v[172:173]
	v_pk_add_f32 v[174:175], v[90:91], v[174:175]
	v_cvt_pk_bf16_f32 v32, v168, v169
	v_cvt_pk_bf16_f32 v33, v170, v171
	v_cvt_pk_bf16_f32 v34, v172, v173
	v_cvt_pk_bf16_f32 v35, v174, v175
	v_cndmask_b32_e32 v32, 0, v32, vcc
	v_cndmask_b32_e32 v33, 0, v33, vcc
	v_cndmask_b32_e32 v34, 0, v34, vcc
	v_cndmask_b32_e32 v35, 0, v35, vcc
	global_load_dwordx4 v[80:83], v124, s[30:31] offset:64
	global_load_dwordx4 v[84:87], v133, s[60:61] offset:128
	global_load_dwordx4 v[88:91], v133, s[60:61] offset:144
	global_load_dwordx4 v[136:139], v125, s[34:35] offset:64
	global_load_dwordx4 v[140:143], v126, s[34:35] offset:64
	global_load_dwordx4 v[144:147], v127, s[34:35] offset:64
	global_load_dwordx4 v[148:151], v128, s[34:35] offset:64
	global_load_dwordx4 v[152:155], v129, s[34:35] offset:64
	global_load_dwordx4 v[156:159], v130, s[34:35] offset:64
	global_load_dwordx4 v[160:163], v131, s[34:35] offset:64
	global_load_dwordx4 v[164:167], v132, s[34:35] offset:64
	s_waitcnt vmcnt(18)
	v_mfma_f32_16x16x32_bf16 v[4:7], v[32:35], v[92:95], v[4:7]
	s_waitcnt vmcnt(17)
	v_mfma_f32_16x16x32_bf16 v[12:15], v[32:35], v[96:99], v[12:15]
	s_waitcnt vmcnt(16)
	v_mfma_f32_16x16x32_bf16 v[8:11], v[32:35], v[100:103], v[8:11]
	s_waitcnt vmcnt(15)
	v_mfma_f32_16x16x32_bf16 v[20:23], v[32:35], v[104:107], v[20:23]
	s_waitcnt vmcnt(14)
	v_mfma_f32_16x16x32_bf16 v[16:19], v[32:35], v[108:111], v[16:19]
	s_waitcnt vmcnt(13)
	v_mfma_f32_16x16x32_bf16 v[28:31], v[32:35], v[112:115], v[28:31]
	s_waitcnt vmcnt(12)
	v_mfma_f32_16x16x32_bf16 v[24:27], v[32:35], v[116:119], v[24:27]
	s_waitcnt vmcnt(11)
	v_mfma_f32_16x16x32_bf16 v[0:3], v[32:35], v[120:123], v[0:3]
	s_waitcnt vmcnt(8)
	v_lshlrev_b32_e32 v168, 16, v80
	v_and_b32_e32 v169, 0xffff0000, v80
	v_lshlrev_b32_e32 v170, 16, v81
	v_and_b32_e32 v171, 0xffff0000, v81
	v_lshlrev_b32_e32 v172, 16, v82
	v_and_b32_e32 v173, 0xffff0000, v82
	v_lshlrev_b32_e32 v174, 16, v83
	v_and_b32_e32 v175, 0xffff0000, v83
	v_pk_add_f32 v[168:169], v[84:85], v[168:169]
	v_pk_add_f32 v[170:171], v[86:87], v[170:171]
	v_pk_add_f32 v[172:173], v[88:89], v[172:173]
	v_pk_add_f32 v[174:175], v[90:91], v[174:175]
	v_cvt_pk_bf16_f32 v32, v168, v169
	v_cvt_pk_bf16_f32 v33, v170, v171
	v_cvt_pk_bf16_f32 v34, v172, v173
	v_cvt_pk_bf16_f32 v35, v174, v175
	v_cndmask_b32_e32 v32, 0, v32, vcc
	v_cndmask_b32_e32 v33, 0, v33, vcc
	v_cndmask_b32_e32 v34, 0, v34, vcc
	v_cndmask_b32_e32 v35, 0, v35, vcc
	global_load_dwordx4 v[80:83], v124, s[30:31] offset:128
	global_load_dwordx4 v[84:87], v133, s[60:61] offset:256
	global_load_dwordx4 v[88:91], v133, s[60:61] offset:272
	global_load_dwordx4 v[92:95], v125, s[34:35] offset:128
	global_load_dwordx4 v[96:99], v126, s[34:35] offset:128
	global_load_dwordx4 v[100:103], v127, s[34:35] offset:128
	global_load_dwordx4 v[104:107], v128, s[34:35] offset:128
	global_load_dwordx4 v[108:111], v129, s[34:35] offset:128
	global_load_dwordx4 v[112:115], v130, s[34:35] offset:128
	global_load_dwordx4 v[116:119], v131, s[34:35] offset:128
	global_load_dwordx4 v[120:123], v132, s[34:35] offset:128
	s_waitcnt vmcnt(18)
; __device__ __forceinline__ float bflo(unsigned u) { return __uint_as_float(u << 16); }
; __device__ __forceinline__ float bfhi(unsigned u) { return __uint_as_float(u & 0xffff0000u); }
; __device__ __forceinline__ void compress_phase(const bf16_t* __restrict__ proj, const float* __restrict__ pos_k, ...
;     ...
;     for (int ks = 0; ks < 16; ++ks) {
;       const int l = w * 4 + (ks >> 2), d0 = (ks & 3) * 32 + quad * 8;
;       bf16x8 a = (bf16x8){0, 0, 0, 0, 0, 0, 0, 0};
;       if (rowvalid) {
;         size_t tokrow = (size_t)b * SEQ + n * 16 + l;
;         uint4 raw = *(const uint4*)(proj + tokrow * NPAD + off + g * 128 + d0);
;         float4 p0 = *(const float4*)(pos + l * 128 + d0), p1 = *(const float4*)(pos + l * 128 + d0 + 4);
;         uint4 pk;
;         pk.x = pack2(bflo(raw.x) + p0.x, bfhi(raw.x) + p0.y);
;         pk.y = pack2(bflo(raw.y) + p0.z, bfhi(raw.y) + p0.w);
;         pk.z = pack2(bflo(raw.z) + p1.x, bfhi(raw.z) + p1.y);
;         pk.w = pack2(bflo(raw.w) + p1.z, bfhi(raw.w) + p1.w);
;         a = *reinterpret_cast<bf16x8*>(&pk);
;       }
; #pragma unroll
;       for (int nt = 0; nt < 8; ++nt) {
;         bf16x8 bw = *(const bf16x8*)(w1t + (size_t)(nt * 16 + c) * 4096 + l * 128 + d0);
;         acc[nt] = __builtin_amdgcn_mfma_f32_16x16x32_bf16(a, bw, acc[nt], 0, 0, 0);
;       }
;     }
	v_mfma_f32_16x16x32_bf16 v[4:7], v[32:35], v[136:139], v[4:7]
	s_waitcnt vmcnt(17)
	v_mfma_f32_16x16x32_bf16 v[12:15], v[32:35], v[140:143], v[12:15]
	s_waitcnt vmcnt(16)
	v_mfma_f32_16x16x32_bf16 v[8:11], v[32:35], v[144:147], v[8:11]
	s_waitcnt vmcnt(15)
	v_mfma_f32_16x16x32_bf16 v[20:23], v[32:35], v[148:151], v[20:23]
	s_waitcnt vmcnt(14)
	v_mfma_f32_16x16x32_bf16 v[16:19], v[32:35], v[152:155], v[16:19]
	s_waitcnt vmcnt(13)
	v_mfma_f32_16x16x32_bf16 v[28:31], v[32:35], v[156:159], v[28:31]
	s_waitcnt vmcnt(12)
	v_mfma_f32_16x16x32_bf16 v[24:27], v[32:35], v[160:163], v[24:27]
	s_waitcnt vmcnt(11)
	v_mfma_f32_16x16x32_bf16 v[0:3], v[32:35], v[164:167], v[0:3]
	s_waitcnt vmcnt(8)
	v_lshlrev_b32_e32 v168, 16, v80
	v_and_b32_e32 v169, 0xffff0000, v80
	v_lshlrev_b32_e32 v170, 16, v81
	v_and_b32_e32 v171, 0xffff0000, v81
	v_lshlrev_b32_e32 v172, 16, v82
	v_and_b32_e32 v173, 0xffff0000, v82
	v_lshlrev_b32_e32 v174, 16, v83
	v_and_b32_e32 v175, 0xffff0000, v83
	v_pk_add_f32 v[168:169], v[84:85], v[168:169]
	v_pk_add_f32 v[170:171], v[86:87], v[170:171]
	v_pk_add_f32 v[172:173], v[88:89], v[172:173]
	v_pk_add_f32 v[174:175], v[90:91], v[174:175]
	v_cvt_pk_bf16_f32 v32, v168, v169
	v_cvt_pk_bf16_f32 v33, v170, v171
	v_cvt_pk_bf16_f32 v34, v172, v173
	v_cvt_pk_bf16_f32 v35, v174, v175
	v_cndmask_b32_e32 v32, 0, v32, vcc
	v_cndmask_b32_e32 v33, 0, v33, vcc
	v_cndmask_b32_e32 v34, 0, v34, vcc
	v_cndmask_b32_e32 v35, 0, v35, vcc
	global_load_dwordx4 v[80:83], v124, s[30:31] offset:192
	global_load_dwordx4 v[84:87], v133, s[60:61] offset:384
	global_load_dwordx4 v[88:91], v133, s[60:61] offset:400
	global_load_dwordx4 v[136:139], v125, s[34:35] offset:192
	global_load_dwordx4 v[140:143], v126, s[34:35] offset:192
	global_load_dwordx4 v[144:147], v127, s[34:35] offset:192
	global_load_dwordx4 v[148:151], v128, s[34:35] offset:192
	global_load_dwordx4 v[152:155], v129, s[34:35] offset:192
	global_load_dwordx4 v[156:159], v130, s[34:35] offset:192
	global_load_dwordx4 v[160:163], v131, s[34:35] offset:192
	global_load_dwordx4 v[164:167], v132, s[34:35] offset:192
	s_waitcnt vmcnt(18)
	v_mfma_f32_16x16x32_bf16 v[4:7], v[32:35], v[92:95], v[4:7]
	s_waitcnt vmcnt(17)
	v_mfma_f32_16x16x32_bf16 v[12:15], v[32:35], v[96:99], v[12:15]
	s_waitcnt vmcnt(16)
	v_mfma_f32_16x16x32_bf16 v[8:11], v[32:35], v[100:103], v[8:11]
	s_waitcnt vmcnt(15)
	v_mfma_f32_16x16x32_bf16 v[20:23], v[32:35], v[104:107], v[20:23]
	s_waitcnt vmcnt(14)
	v_mfma_f32_16x16x32_bf16 v[16:19], v[32:35], v[108:111], v[16:19]
	s_waitcnt vmcnt(13)
	v_mfma_f32_16x16x32_bf16 v[28:31], v[32:35], v[112:115], v[28:31]
	s_waitcnt vmcnt(12)
	v_mfma_f32_16x16x32_bf16 v[24:27], v[32:35], v[116:119], v[24:27]
	s_waitcnt vmcnt(11)
	v_mfma_f32_16x16x32_bf16 v[0:3], v[32:35], v[120:123], v[0:3]
	s_waitcnt vmcnt(8)
	v_lshlrev_b32_e32 v168, 16, v80
	v_and_b32_e32 v169, 0xffff0000, v80
	v_lshlrev_b32_e32 v170, 16, v81
	v_and_b32_e32 v171, 0xffff0000, v81
	v_lshlrev_b32_e32 v172, 16, v82
	v_and_b32_e32 v173, 0xffff0000, v82
	v_lshlrev_b32_e32 v174, 16, v83
	v_and_b32_e32 v175, 0xffff0000, v83
	v_pk_add_f32 v[168:169], v[84:85], v[168:169]
	v_pk_add_f32 v[170:171], v[86:87], v[170:171]
	v_pk_add_f32 v[172:173], v[88:89], v[172:173]
	v_pk_add_f32 v[174:175], v[90:91], v[174:175]
	v_cvt_pk_bf16_f32 v32, v168, v169
	v_cvt_pk_bf16_f32 v33, v170, v171
	v_cvt_pk_bf16_f32 v34, v172, v173
	v_cvt_pk_bf16_f32 v35, v174, v175
	v_cndmask_b32_e32 v32, 0, v32, vcc
	v_cndmask_b32_e32 v33, 0, v33, vcc
	v_cndmask_b32_e32 v34, 0, v34, vcc
	v_cndmask_b32_e32 v35, 0, v35, vcc
	s_add_i32 s10, s38, 1
	s_lshl_b32 s11, s10, 8
	s_add_u32 s34, s28, s11
	s_addc_u32 s35, s29, 0
	s_lshl_b32 s11, s10, 9
	s_add_u32 s60, s56, s11
	s_addc_u32 s61, s57, 0
	v_add_u32_e32 v124, s10, v46
	v_mul_u32_u24_e32 v124, s41, v124
	v_lshl_add_u32 v124, v52, 1, v124
	global_load_dwordx4 v[80:83], v124, s[30:31]
	global_load_dwordx4 v[84:87], v133, s[60:61]
	global_load_dwordx4 v[88:91], v133, s[60:61] offset:16
	global_load_dwordx4 v[92:95], v125, s[34:35]
	global_load_dwordx4 v[96:99], v126, s[34:35]
	global_load_dwordx4 v[100:103], v127, s[34:35]
	global_load_dwordx4 v[104:107], v128, s[34:35]
	global_load_dwordx4 v[108:111], v129, s[34:35]
	global_load_dwordx4 v[112:115], v130, s[34:35]
	global_load_dwordx4 v[116:119], v131, s[34:35]
	global_load_dwordx4 v[120:123], v132, s[34:35]
	s_waitcnt vmcnt(18)
	v_mfma_f32_16x16x32_bf16 v[4:7], v[32:35], v[136:139], v[4:7]
	s_waitcnt vmcnt(17)
	v_mfma_f32_16x16x32_bf16 v[12:15], v[32:35], v[140:143], v[12:15]
	s_waitcnt vmcnt(16)
	v_mfma_f32_16x16x32_bf16 v[8:11], v[32:35], v[144:147], v[8:11]
	s_waitcnt vmcnt(15)
	v_mfma_f32_16x16x32_bf16 v[20:23], v[32:35], v[148:151], v[20:23]
	s_waitcnt vmcnt(14)
	v_mfma_f32_16x16x32_bf16 v[16:19], v[32:35], v[152:155], v[16:19]
	s_waitcnt vmcnt(13)
	v_mfma_f32_16x16x32_bf16 v[28:31], v[32:35], v[156:159], v[28:31]
	s_waitcnt vmcnt(12)
	v_mfma_f32_16x16x32_bf16 v[24:27], v[32:35], v[160:163], v[24:27]
	s_waitcnt vmcnt(11)
	v_mfma_f32_16x16x32_bf16 v[0:3], v[32:35], v[164:167], v[0:3]
	s_waitcnt vmcnt(8)
; __device__ __forceinline__ float bflo(unsigned u) { return __uint_as_float(u << 16); }
; __device__ __forceinline__ float bfhi(unsigned u) { return __uint_as_float(u & 0xffff0000u); }
; __device__ __forceinline__ void compress_phase(const bf16_t* __restrict__ proj, const float* __restrict__ pos_k, ...
;     ...
;     for (int ks = 0; ks < 16; ++ks) {
;       const int l = w * 4 + (ks >> 2), d0 = (ks & 3) * 32 + quad * 8;
;       bf16x8 a = (bf16x8){0, 0, 0, 0, 0, 0, 0, 0};
;       if (rowvalid) {
;         size_t tokrow = (size_t)b * SEQ + n * 16 + l;
;         uint4 raw = *(const uint4*)(proj + tokrow * NPAD + off + g * 128 + d0);
;         float4 p0 = *(const float4*)(pos + l * 128 + d0), p1 = *(const float4*)(pos + l * 128 + d0 + 4);
;         uint4 pk;
;         pk.x = pack2(bflo(raw.x) + p0.x, bfhi(raw.x) + p0.y);
;         pk.y = pack2(bflo(raw.y) + p0.z, bfhi(raw.y) + p0.w);
;         pk.z = pack2(bflo(raw.z) + p1.x, bfhi(raw.z) + p1.y);
;         pk.w = pack2(bflo(raw.w) + p1.z, bfhi(raw.w) + p1.w);
;         a = *reinterpret_cast<bf16x8*>(&pk);
;       }
; #pragma unroll
;       for (int nt = 0; nt < 8; ++nt) {
;         bf16x8 bw = *(const bf16x8*)(w1t + (size_t)(nt * 16 + c) * 4096 + l * 128 + d0);
;         acc[nt] = __builtin_amdgcn_mfma_f32_16x16x32_bf16(a, bw, acc[nt], 0, 0, 0);
;       }
;     }
	v_lshlrev_b32_e32 v168, 16, v80
	v_and_b32_e32 v169, 0xffff0000, v80
	v_lshlrev_b32_e32 v170, 16, v81
	v_and_b32_e32 v171, 0xffff0000, v81
	v_lshlrev_b32_e32 v172, 16, v82
	v_and_b32_e32 v173, 0xffff0000, v82
	v_lshlrev_b32_e32 v174, 16, v83
	v_and_b32_e32 v175, 0xffff0000, v83
	v_pk_add_f32 v[168:169], v[84:85], v[168:169]
	v_pk_add_f32 v[170:171], v[86:87], v[170:171]
	v_pk_add_f32 v[172:173], v[88:89], v[172:173]
	v_pk_add_f32 v[174:175], v[90:91], v[174:175]
	v_cvt_pk_bf16_f32 v32, v168, v169
	v_cvt_pk_bf16_f32 v33, v170, v171
	v_cvt_pk_bf16_f32 v34, v172, v173
	v_cvt_pk_bf16_f32 v35, v174, v175
	v_cndmask_b32_e32 v32, 0, v32, vcc
	v_cndmask_b32_e32 v33, 0, v33, vcc
	v_cndmask_b32_e32 v34, 0, v34, vcc
	v_cndmask_b32_e32 v35, 0, v35, vcc
	global_load_dwordx4 v[80:83], v124, s[30:31] offset:64
	global_load_dwordx4 v[84:87], v133, s[60:61] offset:128
	global_load_dwordx4 v[88:91], v133, s[60:61] offset:144
	global_load_dwordx4 v[136:139], v125, s[34:35] offset:64
	global_load_dwordx4 v[140:143], v126, s[34:35] offset:64
	global_load_dwordx4 v[144:147], v127, s[34:35] offset:64
	global_load_dwordx4 v[148:151], v128, s[34:35] offset:64
	global_load_dwordx4 v[152:155], v129, s[34:35] offset:64
	global_load_dwordx4 v[156:159], v130, s[34:35] offset:64
	global_load_dwordx4 v[160:163], v131, s[34:35] offset:64
	global_load_dwordx4 v[164:167], v132, s[34:35] offset:64
	s_waitcnt vmcnt(18)
	v_mfma_f32_16x16x32_bf16 v[4:7], v[32:35], v[92:95], v[4:7]
	s_waitcnt vmcnt(17)
	v_mfma_f32_16x16x32_bf16 v[12:15], v[32:35], v[96:99], v[12:15]
	s_waitcnt vmcnt(16)
	v_mfma_f32_16x16x32_bf16 v[8:11], v[32:35], v[100:103], v[8:11]
	s_waitcnt vmcnt(15)
	v_mfma_f32_16x16x32_bf16 v[20:23], v[32:35], v[104:107], v[20:23]
	s_waitcnt vmcnt(14)
	v_mfma_f32_16x16x32_bf16 v[16:19], v[32:35], v[108:111], v[16:19]
	s_waitcnt vmcnt(13)
	v_mfma_f32_16x16x32_bf16 v[28:31], v[32:35], v[112:115], v[28:31]
	s_waitcnt vmcnt(12)
	v_mfma_f32_16x16x32_bf16 v[24:27], v[32:35], v[116:119], v[24:27]
	s_waitcnt vmcnt(11)
	v_mfma_f32_16x16x32_bf16 v[0:3], v[32:35], v[120:123], v[0:3]
	s_waitcnt vmcnt(8)
	v_lshlrev_b32_e32 v168, 16, v80
	v_and_b32_e32 v169, 0xffff0000, v80
	v_lshlrev_b32_e32 v170, 16, v81
	v_and_b32_e32 v171, 0xffff0000, v81
	v_lshlrev_b32_e32 v172, 16, v82
	v_and_b32_e32 v173, 0xffff0000, v82
	v_lshlrev_b32_e32 v174, 16, v83
	v_and_b32_e32 v175, 0xffff0000, v83
	v_pk_add_f32 v[168:169], v[84:85], v[168:169]
	v_pk_add_f32 v[170:171], v[86:87], v[170:171]
	v_pk_add_f32 v[172:173], v[88:89], v[172:173]
	v_pk_add_f32 v[174:175], v[90:91], v[174:175]
	v_cvt_pk_bf16_f32 v32, v168, v169
	v_cvt_pk_bf16_f32 v33, v170, v171
	v_cvt_pk_bf16_f32 v34, v172, v173
	v_cvt_pk_bf16_f32 v35, v174, v175
	v_cndmask_b32_e32 v32, 0, v32, vcc
	v_cndmask_b32_e32 v33, 0, v33, vcc
	v_cndmask_b32_e32 v34, 0, v34, vcc
	v_cndmask_b32_e32 v35, 0, v35, vcc
	global_load_dwordx4 v[80:83], v124, s[30:31] offset:128
	global_load_dwordx4 v[84:87], v133, s[60:61] offset:256
	global_load_dwordx4 v[88:91], v133, s[60:61] offset:272
	global_load_dwordx4 v[92:95], v125, s[34:35] offset:128
	global_load_dwordx4 v[96:99], v126, s[34:35] offset:128
	global_load_dwordx4 v[100:103], v127, s[34:35] offset:128
	global_load_dwordx4 v[104:107], v128, s[34:35] offset:128
	global_load_dwordx4 v[108:111], v129, s[34:35] offset:128
	global_load_dwordx4 v[112:115], v130, s[34:35] offset:128
	global_load_dwordx4 v[116:119], v131, s[34:35] offset:128
	global_load_dwordx4 v[120:123], v132, s[34:35] offset:128
	s_waitcnt vmcnt(18)
	v_mfma_f32_16x16x32_bf16 v[4:7], v[32:35], v[136:139], v[4:7]
	s_waitcnt vmcnt(17)
	v_mfma_f32_16x16x32_bf16 v[12:15], v[32:35], v[140:143], v[12:15]
	s_waitcnt vmcnt(16)
	v_mfma_f32_16x16x32_bf16 v[8:11], v[32:35], v[144:147], v[8:11]
	s_waitcnt vmcnt(15)
	v_mfma_f32_16x16x32_bf16 v[20:23], v[32:35], v[148:151], v[20:23]
	s_waitcnt vmcnt(14)
	v_mfma_f32_16x16x32_bf16 v[16:19], v[32:35], v[152:155], v[16:19]
	s_waitcnt vmcnt(13)
	v_mfma_f32_16x16x32_bf16 v[28:31], v[32:35], v[156:159], v[28:31]
	s_waitcnt vmcnt(12)
	v_mfma_f32_16x16x32_bf16 v[24:27], v[32:35], v[160:163], v[24:27]
	s_waitcnt vmcnt(11)
	v_mfma_f32_16x16x32_bf16 v[0:3], v[32:35], v[164:167], v[0:3]
	s_waitcnt vmcnt(8)
	v_lshlrev_b32_e32 v168, 16, v80
	v_and_b32_e32 v169, 0xffff0000, v80
	v_lshlrev_b32_e32 v170, 16, v81
	v_and_b32_e32 v171, 0xffff0000, v81
	v_lshlrev_b32_e32 v172, 16, v82
	v_and_b32_e32 v173, 0xffff0000, v82
	v_lshlrev_b32_e32 v174, 16, v83
	v_and_b32_e32 v175, 0xffff0000, v83
	v_pk_add_f32 v[168:169], v[84:85], v[168:169]
	v_pk_add_f32 v[170:171], v[86:87], v[170:171]
	v_pk_add_f32 v[172:173], v[88:89], v[172:173]
	v_pk_add_f32 v[174:175], v[90:91], v[174:175]
	v_cvt_pk_bf16_f32 v32, v168, v169
	v_cvt_pk_bf16_f32 v33, v170, v171
	v_cvt_pk_bf16_f32 v34, v172, v173
	v_cvt_pk_bf16_f32 v35, v174, v175
	v_cndmask_b32_e32 v32, 0, v32, vcc
	v_cndmask_b32_e32 v33, 0, v33, vcc
	v_cndmask_b32_e32 v34, 0, v34, vcc
	v_cndmask_b32_e32 v35, 0, v35, vcc
	global_load_dwordx4 v[80:83], v124, s[30:31] offset:192
	global_load_dwordx4 v[84:87], v133, s[60:61] offset:384
	global_load_dwordx4 v[88:91], v133, s[60:61] offset:400
	global_load_dwordx4 v[136:139], v125, s[34:35] offset:192
	global_load_dwordx4 v[140:143], v126, s[34:35] offset:192
	global_load_dwordx4 v[144:147], v127, s[34:35] offset:192
	global_load_dwordx4 v[148:151], v128, s[34:35] offset:192
	global_load_dwordx4 v[152:155], v129, s[34:35] offset:192
	global_load_dwordx4 v[156:159], v130, s[34:35] offset:192
	global_load_dwordx4 v[160:163], v131, s[34:35] offset:192
	global_load_dwordx4 v[164:167], v132, s[34:35] offset:192
	s_waitcnt vmcnt(18)
; __device__ __forceinline__ float bflo(unsigned u) { return __uint_as_float(u << 16); }
; __device__ __forceinline__ float bfhi(unsigned u) { return __uint_as_float(u & 0xffff0000u); }
; __device__ __forceinline__ void compress_phase(const bf16_t* __restrict__ proj, const float* __restrict__ pos_k, ...
;     ...
;     for (int ks = 0; ks < 16; ++ks) {
;       const int l = w * 4 + (ks >> 2), d0 = (ks & 3) * 32 + quad * 8;
;       bf16x8 a = (bf16x8){0, 0, 0, 0, 0, 0, 0, 0};
;       if (rowvalid) {
;         size_t tokrow = (size_t)b * SEQ + n * 16 + l;
;         uint4 raw = *(const uint4*)(proj + tokrow * NPAD + off + g * 128 + d0);
;         float4 p0 = *(const float4*)(pos + l * 128 + d0), p1 = *(const float4*)(pos + l * 128 + d0 + 4);
;         uint4 pk;
;         pk.x = pack2(bflo(raw.x) + p0.x, bfhi(raw.x) + p0.y);
;         pk.y = pack2(bflo(raw.y) + p0.z, bfhi(raw.y) + p0.w);
;         pk.z = pack2(bflo(raw.z) + p1.x, bfhi(raw.z) + p1.y);
;         pk.w = pack2(bflo(raw.w) + p1.z, bfhi(raw.w) + p1.w);
;         a = *reinterpret_cast<bf16x8*>(&pk);
;       }
; #pragma unroll
;       for (int nt = 0; nt < 8; ++nt) {
;         bf16x8 bw = *(const bf16x8*)(w1t + (size_t)(nt * 16 + c) * 4096 + l * 128 + d0);
;         acc[nt] = __builtin_amdgcn_mfma_f32_16x16x32_bf16(a, bw, acc[nt], 0, 0, 0);
;       }
;     }
	v_mfma_f32_16x16x32_bf16 v[4:7], v[32:35], v[92:95], v[4:7]
	s_waitcnt vmcnt(17)
	v_mfma_f32_16x16x32_bf16 v[12:15], v[32:35], v[96:99], v[12:15]
	s_waitcnt vmcnt(16)
	v_mfma_f32_16x16x32_bf16 v[8:11], v[32:35], v[100:103], v[8:11]
	s_waitcnt vmcnt(15)
	v_mfma_f32_16x16x32_bf16 v[20:23], v[32:35], v[104:107], v[20:23]
	s_waitcnt vmcnt(14)
	v_mfma_f32_16x16x32_bf16 v[16:19], v[32:35], v[108:111], v[16:19]
	s_waitcnt vmcnt(13)
	v_mfma_f32_16x16x32_bf16 v[28:31], v[32:35], v[112:115], v[28:31]
	s_waitcnt vmcnt(12)
	v_mfma_f32_16x16x32_bf16 v[24:27], v[32:35], v[116:119], v[24:27]
	s_waitcnt vmcnt(11)
	v_mfma_f32_16x16x32_bf16 v[0:3], v[32:35], v[120:123], v[0:3]
	s_waitcnt vmcnt(8)
	v_lshlrev_b32_e32 v168, 16, v80
	v_and_b32_e32 v169, 0xffff0000, v80
	v_lshlrev_b32_e32 v170, 16, v81
	v_and_b32_e32 v171, 0xffff0000, v81
	v_lshlrev_b32_e32 v172, 16, v82
	v_and_b32_e32 v173, 0xffff0000, v82
	v_lshlrev_b32_e32 v174, 16, v83
	v_and_b32_e32 v175, 0xffff0000, v83
	v_pk_add_f32 v[168:169], v[84:85], v[168:169]
	v_pk_add_f32 v[170:171], v[86:87], v[170:171]
	v_pk_add_f32 v[172:173], v[88:89], v[172:173]
	v_pk_add_f32 v[174:175], v[90:91], v[174:175]
	v_cvt_pk_bf16_f32 v32, v168, v169
	v_cvt_pk_bf16_f32 v33, v170, v171
	v_cvt_pk_bf16_f32 v34, v172, v173
	v_cvt_pk_bf16_f32 v35, v174, v175
	v_cndmask_b32_e32 v32, 0, v32, vcc
	v_cndmask_b32_e32 v33, 0, v33, vcc
	v_cndmask_b32_e32 v34, 0, v34, vcc
	v_cndmask_b32_e32 v35, 0, v35, vcc
	s_add_i32 s10, s38, 2
	s_lshl_b32 s11, s10, 8
	s_add_u32 s34, s28, s11
	s_addc_u32 s35, s29, 0
	s_lshl_b32 s11, s10, 9
	s_add_u32 s60, s56, s11
	s_addc_u32 s61, s57, 0
	v_add_u32_e32 v124, s10, v46
	v_mul_u32_u24_e32 v124, s41, v124
	v_lshl_add_u32 v124, v52, 1, v124
	global_load_dwordx4 v[80:83], v124, s[30:31]
	global_load_dwordx4 v[84:87], v133, s[60:61]
	global_load_dwordx4 v[88:91], v133, s[60:61] offset:16
	global_load_dwordx4 v[92:95], v125, s[34:35]
	global_load_dwordx4 v[96:99], v126, s[34:35]
	global_load_dwordx4 v[100:103], v127, s[34:35]
	global_load_dwordx4 v[104:107], v128, s[34:35]
	global_load_dwordx4 v[108:111], v129, s[34:35]
	global_load_dwordx4 v[112:115], v130, s[34:35]
	global_load_dwordx4 v[116:119], v131, s[34:35]
	global_load_dwordx4 v[120:123], v132, s[34:35]
	s_waitcnt vmcnt(18)
	v_mfma_f32_16x16x32_bf16 v[4:7], v[32:35], v[136:139], v[4:7]
	s_waitcnt vmcnt(17)
	v_mfma_f32_16x16x32_bf16 v[12:15], v[32:35], v[140:143], v[12:15]
	s_waitcnt vmcnt(16)
	v_mfma_f32_16x16x32_bf16 v[8:11], v[32:35], v[144:147], v[8:11]
	s_waitcnt vmcnt(15)
	v_mfma_f32_16x16x32_bf16 v[20:23], v[32:35], v[148:151], v[20:23]
	s_waitcnt vmcnt(14)
	v_mfma_f32_16x16x32_bf16 v[16:19], v[32:35], v[152:155], v[16:19]
	s_waitcnt vmcnt(13)
	v_mfma_f32_16x16x32_bf16 v[28:31], v[32:35], v[156:159], v[28:31]
	s_waitcnt vmcnt(12)
	v_mfma_f32_16x16x32_bf16 v[24:27], v[32:35], v[160:163], v[24:27]
	s_waitcnt vmcnt(11)
	v_mfma_f32_16x16x32_bf16 v[0:3], v[32:35], v[164:167], v[0:3]
	s_waitcnt vmcnt(8)
	v_lshlrev_b32_e32 v168, 16, v80
	v_and_b32_e32 v169, 0xffff0000, v80
	v_lshlrev_b32_e32 v170, 16, v81
	v_and_b32_e32 v171, 0xffff0000, v81
	v_lshlrev_b32_e32 v172, 16, v82
	v_and_b32_e32 v173, 0xffff0000, v82
	v_lshlrev_b32_e32 v174, 16, v83
	v_and_b32_e32 v175, 0xffff0000, v83
	v_pk_add_f32 v[168:169], v[84:85], v[168:169]
	v_pk_add_f32 v[170:171], v[86:87], v[170:171]
	v_pk_add_f32 v[172:173], v[88:89], v[172:173]
	v_pk_add_f32 v[174:175], v[90:91], v[174:175]
	v_cvt_pk_bf16_f32 v32, v168, v169
	v_cvt_pk_bf16_f32 v33, v170, v171
	v_cvt_pk_bf16_f32 v34, v172, v173
	v_cvt_pk_bf16_f32 v35, v174, v175
	v_cndmask_b32_e32 v32, 0, v32, vcc
	v_cndmask_b32_e32 v33, 0, v33, vcc
	v_cndmask_b32_e32 v34, 0, v34, vcc
	v_cndmask_b32_e32 v35, 0, v35, vcc
	global_load_dwordx4 v[80:83], v124, s[30:31] offset:64
	global_load_dwordx4 v[84:87], v133, s[60:61] offset:128
	global_load_dwordx4 v[88:91], v133, s[60:61] offset:144
	global_load_dwordx4 v[136:139], v125, s[34:35] offset:64
	global_load_dwordx4 v[140:143], v126, s[34:35] offset:64
	global_load_dwordx4 v[144:147], v127, s[34:35] offset:64
	global_load_dwordx4 v[148:151], v128, s[34:35] offset:64
	global_load_dwordx4 v[152:155], v129, s[34:35] offset:64
	global_load_dwordx4 v[156:159], v130, s[34:35] offset:64
	global_load_dwordx4 v[160:163], v131, s[34:35] offset:64
	global_load_dwordx4 v[164:167], v132, s[34:35] offset:64
	s_waitcnt vmcnt(18)
	v_mfma_f32_16x16x32_bf16 v[4:7], v[32:35], v[92:95], v[4:7]
	s_waitcnt vmcnt(17)
	v_mfma_f32_16x16x32_bf16 v[12:15], v[32:35], v[96:99], v[12:15]
	s_waitcnt vmcnt(16)
	v_mfma_f32_16x16x32_bf16 v[8:11], v[32:35], v[100:103], v[8:11]
	s_waitcnt vmcnt(15)
	v_mfma_f32_16x16x32_bf16 v[20:23], v[32:35], v[104:107], v[20:23]
	s_waitcnt vmcnt(14)
	v_mfma_f32_16x16x32_bf16 v[16:19], v[32:35], v[108:111], v[16:19]
	s_waitcnt vmcnt(13)
	v_mfma_f32_16x16x32_bf16 v[28:31], v[32:35], v[112:115], v[28:31]
	s_waitcnt vmcnt(12)
	v_mfma_f32_16x16x32_bf16 v[24:27], v[32:35], v[116:119], v[24:27]
	s_waitcnt vmcnt(11)
	v_mfma_f32_16x16x32_bf16 v[0:3], v[32:35], v[120:123], v[0:3]
	s_waitcnt vmcnt(8)
; __device__ __forceinline__ float bflo(unsigned u) { return __uint_as_float(u << 16); }
; __device__ __forceinline__ float bfhi(unsigned u) { return __uint_as_float(u & 0xffff0000u); }
; __device__ __forceinline__ void compress_phase(const bf16_t* __restrict__ proj, const float* __restrict__ pos_k, ...
;     ...
;     for (int ks = 0; ks < 16; ++ks) {
;       const int l = w * 4 + (ks >> 2), d0 = (ks & 3) * 32 + quad * 8;
;       bf16x8 a = (bf16x8){0, 0, 0, 0, 0, 0, 0, 0};
;       if (rowvalid) {
;         size_t tokrow = (size_t)b * SEQ + n * 16 + l;
;         uint4 raw = *(const uint4*)(proj + tokrow * NPAD + off + g * 128 + d0);
;         float4 p0 = *(const float4*)(pos + l * 128 + d0), p1 = *(const float4*)(pos + l * 128 + d0 + 4);
;         uint4 pk;
;         pk.x = pack2(bflo(raw.x) + p0.x, bfhi(raw.x) + p0.y);
;         pk.y = pack2(bflo(raw.y) + p0.z, bfhi(raw.y) + p0.w);
;         pk.z = pack2(bflo(raw.z) + p1.x, bfhi(raw.z) + p1.y);
;         pk.w = pack2(bflo(raw.w) + p1.z, bfhi(raw.w) + p1.w);
;         a = *reinterpret_cast<bf16x8*>(&pk);
;       }
; #pragma unroll
;       for (int nt = 0; nt < 8; ++nt) {
;         bf16x8 bw = *(const bf16x8*)(w1t + (size_t)(nt * 16 + c) * 4096 + l * 128 + d0);
;         acc[nt] = __builtin_amdgcn_mfma_f32_16x16x32_bf16(a, bw, acc[nt], 0, 0, 0);
;       }
;     }
	v_lshlrev_b32_e32 v168, 16, v80
	v_and_b32_e32 v169, 0xffff0000, v80
	v_lshlrev_b32_e32 v170, 16, v81
	v_and_b32_e32 v171, 0xffff0000, v81
	v_lshlrev_b32_e32 v172, 16, v82
	v_and_b32_e32 v173, 0xffff0000, v82
	v_lshlrev_b32_e32 v174, 16, v83
	v_and_b32_e32 v175, 0xffff0000, v83
	v_pk_add_f32 v[168:169], v[84:85], v[168:169]
	v_pk_add_f32 v[170:171], v[86:87], v[170:171]
	v_pk_add_f32 v[172:173], v[88:89], v[172:173]
	v_pk_add_f32 v[174:175], v[90:91], v[174:175]
	v_cvt_pk_bf16_f32 v32, v168, v169
	v_cvt_pk_bf16_f32 v33, v170, v171
	v_cvt_pk_bf16_f32 v34, v172, v173
	v_cvt_pk_bf16_f32 v35, v174, v175
	v_cndmask_b32_e32 v32, 0, v32, vcc
	v_cndmask_b32_e32 v33, 0, v33, vcc
	v_cndmask_b32_e32 v34, 0, v34, vcc
	v_cndmask_b32_e32 v35, 0, v35, vcc
	global_load_dwordx4 v[80:83], v124, s[30:31] offset:128
	global_load_dwordx4 v[84:87], v133, s[60:61] offset:256
	global_load_dwordx4 v[88:91], v133, s[60:61] offset:272
	global_load_dwordx4 v[92:95], v125, s[34:35] offset:128
	global_load_dwordx4 v[96:99], v126, s[34:35] offset:128
	global_load_dwordx4 v[100:103], v127, s[34:35] offset:128
	global_load_dwordx4 v[104:107], v128, s[34:35] offset:128
	global_load_dwordx4 v[108:111], v129, s[34:35] offset:128
	global_load_dwordx4 v[112:115], v130, s[34:35] offset:128
	global_load_dwordx4 v[116:119], v131, s[34:35] offset:128
	global_load_dwordx4 v[120:123], v132, s[34:35] offset:128
	s_waitcnt vmcnt(18)
	v_mfma_f32_16x16x32_bf16 v[4:7], v[32:35], v[136:139], v[4:7]
	s_waitcnt vmcnt(17)
	v_mfma_f32_16x16x32_bf16 v[12:15], v[32:35], v[140:143], v[12:15]
	s_waitcnt vmcnt(16)
	v_mfma_f32_16x16x32_bf16 v[8:11], v[32:35], v[144:147], v[8:11]
	s_waitcnt vmcnt(15)
	v_mfma_f32_16x16x32_bf16 v[20:23], v[32:35], v[148:151], v[20:23]
	s_waitcnt vmcnt(14)
	v_mfma_f32_16x16x32_bf16 v[16:19], v[32:35], v[152:155], v[16:19]
	s_waitcnt vmcnt(13)
	v_mfma_f32_16x16x32_bf16 v[28:31], v[32:35], v[156:159], v[28:31]
	s_waitcnt vmcnt(12)
	v_mfma_f32_16x16x32_bf16 v[24:27], v[32:35], v[160:163], v[24:27]
	s_waitcnt vmcnt(11)
	v_mfma_f32_16x16x32_bf16 v[0:3], v[32:35], v[164:167], v[0:3]
	s_waitcnt vmcnt(8)
	v_lshlrev_b32_e32 v168, 16, v80
	v_and_b32_e32 v169, 0xffff0000, v80
	v_lshlrev_b32_e32 v170, 16, v81
	v_and_b32_e32 v171, 0xffff0000, v81
	v_lshlrev_b32_e32 v172, 16, v82
	v_and_b32_e32 v173, 0xffff0000, v82
	v_lshlrev_b32_e32 v174, 16, v83
	v_and_b32_e32 v175, 0xffff0000, v83
	v_pk_add_f32 v[168:169], v[84:85], v[168:169]
	v_pk_add_f32 v[170:171], v[86:87], v[170:171]
	v_pk_add_f32 v[172:173], v[88:89], v[172:173]
	v_pk_add_f32 v[174:175], v[90:91], v[174:175]
	v_cvt_pk_bf16_f32 v32, v168, v169
	v_cvt_pk_bf16_f32 v33, v170, v171
	v_cvt_pk_bf16_f32 v34, v172, v173
	v_cvt_pk_bf16_f32 v35, v174, v175
	v_cndmask_b32_e32 v32, 0, v32, vcc
	v_cndmask_b32_e32 v33, 0, v33, vcc
	v_cndmask_b32_e32 v34, 0, v34, vcc
	v_cndmask_b32_e32 v35, 0, v35, vcc
	global_load_dwordx4 v[80:83], v124, s[30:31] offset:192
	global_load_dwordx4 v[84:87], v133, s[60:61] offset:384
	global_load_dwordx4 v[88:91], v133, s[60:61] offset:400
	global_load_dwordx4 v[136:139], v125, s[34:35] offset:192
	global_load_dwordx4 v[140:143], v126, s[34:35] offset:192
	global_load_dwordx4 v[144:147], v127, s[34:35] offset:192
	global_load_dwordx4 v[148:151], v128, s[34:35] offset:192
	global_load_dwordx4 v[152:155], v129, s[34:35] offset:192
	global_load_dwordx4 v[156:159], v130, s[34:35] offset:192
	global_load_dwordx4 v[160:163], v131, s[34:35] offset:192
	global_load_dwordx4 v[164:167], v132, s[34:35] offset:192
	s_waitcnt vmcnt(18)
	v_mfma_f32_16x16x32_bf16 v[4:7], v[32:35], v[92:95], v[4:7]
	s_waitcnt vmcnt(17)
	v_mfma_f32_16x16x32_bf16 v[12:15], v[32:35], v[96:99], v[12:15]
	s_waitcnt vmcnt(16)
	v_mfma_f32_16x16x32_bf16 v[8:11], v[32:35], v[100:103], v[8:11]
	s_waitcnt vmcnt(15)
	v_mfma_f32_16x16x32_bf16 v[20:23], v[32:35], v[104:107], v[20:23]
	s_waitcnt vmcnt(14)
	v_mfma_f32_16x16x32_bf16 v[16:19], v[32:35], v[108:111], v[16:19]
	s_waitcnt vmcnt(13)
	v_mfma_f32_16x16x32_bf16 v[28:31], v[32:35], v[112:115], v[28:31]
	s_waitcnt vmcnt(12)
	v_mfma_f32_16x16x32_bf16 v[24:27], v[32:35], v[116:119], v[24:27]
	s_waitcnt vmcnt(11)
	v_mfma_f32_16x16x32_bf16 v[0:3], v[32:35], v[120:123], v[0:3]
	s_waitcnt vmcnt(8)
	v_lshlrev_b32_e32 v168, 16, v80
	v_and_b32_e32 v169, 0xffff0000, v80
	v_lshlrev_b32_e32 v170, 16, v81
	v_and_b32_e32 v171, 0xffff0000, v81
	v_lshlrev_b32_e32 v172, 16, v82
	v_and_b32_e32 v173, 0xffff0000, v82
	v_lshlrev_b32_e32 v174, 16, v83
	v_and_b32_e32 v175, 0xffff0000, v83
	v_pk_add_f32 v[168:169], v[84:85], v[168:169]
	v_pk_add_f32 v[170:171], v[86:87], v[170:171]
	v_pk_add_f32 v[172:173], v[88:89], v[172:173]
	v_pk_add_f32 v[174:175], v[90:91], v[174:175]
	v_cvt_pk_bf16_f32 v32, v168, v169
	v_cvt_pk_bf16_f32 v33, v170, v171
	v_cvt_pk_bf16_f32 v34, v172, v173
	v_cvt_pk_bf16_f32 v35, v174, v175
	v_cndmask_b32_e32 v32, 0, v32, vcc
	v_cndmask_b32_e32 v33, 0, v33, vcc
	v_cndmask_b32_e32 v34, 0, v34, vcc
	v_cndmask_b32_e32 v35, 0, v35, vcc
	s_add_i32 s10, s38, 3
	s_lshl_b32 s11, s10, 8
	s_add_u32 s34, s28, s11
	s_addc_u32 s35, s29, 0
	s_lshl_b32 s11, s10, 9
	s_add_u32 s60, s56, s11
	s_addc_u32 s61, s57, 0
	v_add_u32_e32 v124, s10, v46
	v_mul_u32_u24_e32 v124, s41, v124
	v_lshl_add_u32 v124, v52, 1, v124
	global_load_dwordx4 v[80:83], v124, s[30:31]
	global_load_dwordx4 v[84:87], v133, s[60:61]
	global_load_dwordx4 v[88:91], v133, s[60:61] offset:16
	global_load_dwordx4 v[92:95], v125, s[34:35]
	global_load_dwordx4 v[96:99], v126, s[34:35]
	global_load_dwordx4 v[100:103], v127, s[34:35]
	global_load_dwordx4 v[104:107], v128, s[34:35]
	global_load_dwordx4 v[108:111], v129, s[34:35]
	global_load_dwordx4 v[112:115], v130, s[34:35]
	global_load_dwordx4 v[116:119], v131, s[34:35]
	global_load_dwordx4 v[120:123], v132, s[34:35]
	s_waitcnt vmcnt(18)
; __device__ __forceinline__ float bflo(unsigned u) { return __uint_as_float(u << 16); }
; __device__ __forceinline__ float bfhi(unsigned u) { return __uint_as_float(u & 0xffff0000u); }
; __device__ __forceinline__ void compress_phase(const bf16_t* __restrict__ proj, const float* __restrict__ pos_k, ...
;     ...
;     for (int ks = 0; ks < 16; ++ks) {
;       const int l = w * 4 + (ks >> 2), d0 = (ks & 3) * 32 + quad * 8;
;       bf16x8 a = (bf16x8){0, 0, 0, 0, 0, 0, 0, 0};
;       if (rowvalid) {
;         size_t tokrow = (size_t)b * SEQ + n * 16 + l;
;         uint4 raw = *(const uint4*)(proj + tokrow * NPAD + off + g * 128 + d0);
;         float4 p0 = *(const float4*)(pos + l * 128 + d0), p1 = *(const float4*)(pos + l * 128 + d0 + 4);
;         uint4 pk;
;         pk.x = pack2(bflo(raw.x) + p0.x, bfhi(raw.x) + p0.y);
;         pk.y = pack2(bflo(raw.y) + p0.z, bfhi(raw.y) + p0.w);
;         pk.z = pack2(bflo(raw.z) + p1.x, bfhi(raw.z) + p1.y);
;         pk.w = pack2(bflo(raw.w) + p1.z, bfhi(raw.w) + p1.w);
;         a = *reinterpret_cast<bf16x8*>(&pk);
;       }
; #pragma unroll
;       for (int nt = 0; nt < 8; ++nt) {
;         bf16x8 bw = *(const bf16x8*)(w1t + (size_t)(nt * 16 + c) * 4096 + l * 128 + d0);
;         acc[nt] = __builtin_amdgcn_mfma_f32_16x16x32_bf16(a, bw, acc[nt], 0, 0, 0);
;       }
;     }
	v_mfma_f32_16x16x32_bf16 v[4:7], v[32:35], v[136:139], v[4:7]
	s_waitcnt vmcnt(17)
	v_mfma_f32_16x16x32_bf16 v[12:15], v[32:35], v[140:143], v[12:15]
	s_waitcnt vmcnt(16)
	v_mfma_f32_16x16x32_bf16 v[8:11], v[32:35], v[144:147], v[8:11]
	s_waitcnt vmcnt(15)
	v_mfma_f32_16x16x32_bf16 v[20:23], v[32:35], v[148:151], v[20:23]
	s_waitcnt vmcnt(14)
	v_mfma_f32_16x16x32_bf16 v[16:19], v[32:35], v[152:155], v[16:19]
	s_waitcnt vmcnt(13)
	v_mfma_f32_16x16x32_bf16 v[28:31], v[32:35], v[156:159], v[28:31]
	s_waitcnt vmcnt(12)
	v_mfma_f32_16x16x32_bf16 v[24:27], v[32:35], v[160:163], v[24:27]
	s_waitcnt vmcnt(11)
	v_mfma_f32_16x16x32_bf16 v[0:3], v[32:35], v[164:167], v[0:3]
	s_waitcnt vmcnt(8)
	v_lshlrev_b32_e32 v168, 16, v80
	v_and_b32_e32 v169, 0xffff0000, v80
	v_lshlrev_b32_e32 v170, 16, v81
	v_and_b32_e32 v171, 0xffff0000, v81
	v_lshlrev_b32_e32 v172, 16, v82
	v_and_b32_e32 v173, 0xffff0000, v82
	v_lshlrev_b32_e32 v174, 16, v83
	v_and_b32_e32 v175, 0xffff0000, v83
	v_pk_add_f32 v[168:169], v[84:85], v[168:169]
	v_pk_add_f32 v[170:171], v[86:87], v[170:171]
	v_pk_add_f32 v[172:173], v[88:89], v[172:173]
	v_pk_add_f32 v[174:175], v[90:91], v[174:175]
	v_cvt_pk_bf16_f32 v32, v168, v169
	v_cvt_pk_bf16_f32 v33, v170, v171
	v_cvt_pk_bf16_f32 v34, v172, v173
	v_cvt_pk_bf16_f32 v35, v174, v175
	v_cndmask_b32_e32 v32, 0, v32, vcc
	v_cndmask_b32_e32 v33, 0, v33, vcc
	v_cndmask_b32_e32 v34, 0, v34, vcc
	v_cndmask_b32_e32 v35, 0, v35, vcc
	global_load_dwordx4 v[80:83], v124, s[30:31] offset:64
	global_load_dwordx4 v[84:87], v133, s[60:61] offset:128
	global_load_dwordx4 v[88:91], v133, s[60:61] offset:144
	global_load_dwordx4 v[136:139], v125, s[34:35] offset:64
	global_load_dwordx4 v[140:143], v126, s[34:35] offset:64
	global_load_dwordx4 v[144:147], v127, s[34:35] offset:64
	global_load_dwordx4 v[148:151], v128, s[34:35] offset:64
	global_load_dwordx4 v[152:155], v129, s[34:35] offset:64
	global_load_dwordx4 v[156:159], v130, s[34:35] offset:64
	global_load_dwordx4 v[160:163], v131, s[34:35] offset:64
	global_load_dwordx4 v[164:167], v132, s[34:35] offset:64
	s_waitcnt vmcnt(18)
	v_mfma_f32_16x16x32_bf16 v[4:7], v[32:35], v[92:95], v[4:7]
	s_waitcnt vmcnt(17)
	v_mfma_f32_16x16x32_bf16 v[12:15], v[32:35], v[96:99], v[12:15]
	s_waitcnt vmcnt(16)
	v_mfma_f32_16x16x32_bf16 v[8:11], v[32:35], v[100:103], v[8:11]
	s_waitcnt vmcnt(15)
	v_mfma_f32_16x16x32_bf16 v[20:23], v[32:35], v[104:107], v[20:23]
	s_waitcnt vmcnt(14)
	v_mfma_f32_16x16x32_bf16 v[16:19], v[32:35], v[108:111], v[16:19]
	s_waitcnt vmcnt(13)
	v_mfma_f32_16x16x32_bf16 v[28:31], v[32:35], v[112:115], v[28:31]
	s_waitcnt vmcnt(12)
	v_mfma_f32_16x16x32_bf16 v[24:27], v[32:35], v[116:119], v[24:27]
	s_waitcnt vmcnt(11)
	v_mfma_f32_16x16x32_bf16 v[0:3], v[32:35], v[120:123], v[0:3]
	s_waitcnt vmcnt(8)
	v_lshlrev_b32_e32 v168, 16, v80
	v_and_b32_e32 v169, 0xffff0000, v80
	v_lshlrev_b32_e32 v170, 16, v81
	v_and_b32_e32 v171, 0xffff0000, v81
	v_lshlrev_b32_e32 v172, 16, v82
	v_and_b32_e32 v173, 0xffff0000, v82
	v_lshlrev_b32_e32 v174, 16, v83
	v_and_b32_e32 v175, 0xffff0000, v83
	v_pk_add_f32 v[168:169], v[84:85], v[168:169]
	v_pk_add_f32 v[170:171], v[86:87], v[170:171]
	v_pk_add_f32 v[172:173], v[88:89], v[172:173]
	v_pk_add_f32 v[174:175], v[90:91], v[174:175]
	v_cvt_pk_bf16_f32 v32, v168, v169
	v_cvt_pk_bf16_f32 v33, v170, v171
	v_cvt_pk_bf16_f32 v34, v172, v173
	v_cvt_pk_bf16_f32 v35, v174, v175
	v_cndmask_b32_e32 v32, 0, v32, vcc
	v_cndmask_b32_e32 v33, 0, v33, vcc
	v_cndmask_b32_e32 v34, 0, v34, vcc
	v_cndmask_b32_e32 v35, 0, v35, vcc
	global_load_dwordx4 v[80:83], v124, s[30:31] offset:128
	global_load_dwordx4 v[84:87], v133, s[60:61] offset:256
	global_load_dwordx4 v[88:91], v133, s[60:61] offset:272
	global_load_dwordx4 v[92:95], v125, s[34:35] offset:128
	global_load_dwordx4 v[96:99], v126, s[34:35] offset:128
	global_load_dwordx4 v[100:103], v127, s[34:35] offset:128
	global_load_dwordx4 v[104:107], v128, s[34:35] offset:128
	global_load_dwordx4 v[108:111], v129, s[34:35] offset:128
	global_load_dwordx4 v[112:115], v130, s[34:35] offset:128
	global_load_dwordx4 v[116:119], v131, s[34:35] offset:128
	global_load_dwordx4 v[120:123], v132, s[34:35] offset:128
	s_waitcnt vmcnt(18)
; __device__ __forceinline__ float bflo(unsigned u) { return __uint_as_float(u << 16); }
; __device__ __forceinline__ float bfhi(unsigned u) { return __uint_as_float(u & 0xffff0000u); }
; __device__ __forceinline__ void compress_phase(const bf16_t* __restrict__ proj, const float* __restrict__ pos_k, ...
;     ...
;     for (int ks = 0; ks < 16; ++ks) {
;       const int l = w * 4 + (ks >> 2), d0 = (ks & 3) * 32 + quad * 8;
;       bf16x8 a = (bf16x8){0, 0, 0, 0, 0, 0, 0, 0};
;       if (rowvalid) {
;         size_t tokrow = (size_t)b * SEQ + n * 16 + l;
;         uint4 raw = *(const uint4*)(proj + tokrow * NPAD + off + g * 128 + d0);
;         float4 p0 = *(const float4*)(pos + l * 128 + d0), p1 = *(const float4*)(pos + l * 128 + d0 + 4);
;         uint4 pk;
;         pk.x = pack2(bflo(raw.x) + p0.x, bfhi(raw.x) + p0.y);
;         pk.y = pack2(bflo(raw.y) + p0.z, bfhi(raw.y) + p0.w);
;         pk.z = pack2(bflo(raw.z) + p1.x, bfhi(raw.z) + p1.y);
;         pk.w = pack2(bflo(raw.w) + p1.z, bfhi(raw.w) + p1.w);
;         a = *reinterpret_cast<bf16x8*>(&pk);
;       }
; #pragma unroll
;       for (int nt = 0; nt < 8; ++nt) {
;         bf16x8 bw = *(const bf16x8*)(w1t + (size_t)(nt * 16 + c) * 4096 + l * 128 + d0);
;         acc[nt] = __builtin_amdgcn_mfma_f32_16x16x32_bf16(a, bw, acc[nt], 0, 0, 0);
;       }
;     }
	v_mfma_f32_16x16x32_bf16 v[4:7], v[32:35], v[136:139], v[4:7]
	s_waitcnt vmcnt(17)
	v_mfma_f32_16x16x32_bf16 v[12:15], v[32:35], v[140:143], v[12:15]
	s_waitcnt vmcnt(16)
	v_mfma_f32_16x16x32_bf16 v[8:11], v[32:35], v[144:147], v[8:11]
	s_waitcnt vmcnt(15)
	v_mfma_f32_16x16x32_bf16 v[20:23], v[32:35], v[148:151], v[20:23]
	s_waitcnt vmcnt(14)
	v_mfma_f32_16x16x32_bf16 v[16:19], v[32:35], v[152:155], v[16:19]
	s_waitcnt vmcnt(13)
	v_mfma_f32_16x16x32_bf16 v[28:31], v[32:35], v[156:159], v[28:31]
	s_waitcnt vmcnt(12)
	v_mfma_f32_16x16x32_bf16 v[24:27], v[32:35], v[160:163], v[24:27]
	s_waitcnt vmcnt(11)
	v_mfma_f32_16x16x32_bf16 v[0:3], v[32:35], v[164:167], v[0:3]
	s_waitcnt vmcnt(8)
	v_lshlrev_b32_e32 v168, 16, v80
	v_and_b32_e32 v169, 0xffff0000, v80
	v_lshlrev_b32_e32 v170, 16, v81
	v_and_b32_e32 v171, 0xffff0000, v81
	v_lshlrev_b32_e32 v172, 16, v82
	v_and_b32_e32 v173, 0xffff0000, v82
	v_lshlrev_b32_e32 v174, 16, v83
	v_and_b32_e32 v175, 0xffff0000, v83
	v_pk_add_f32 v[168:169], v[84:85], v[168:169]
	v_pk_add_f32 v[170:171], v[86:87], v[170:171]
	v_pk_add_f32 v[172:173], v[88:89], v[172:173]
	v_pk_add_f32 v[174:175], v[90:91], v[174:175]
	v_cvt_pk_bf16_f32 v32, v168, v169
	v_cvt_pk_bf16_f32 v33, v170, v171
	v_cvt_pk_bf16_f32 v34, v172, v173
	v_cvt_pk_bf16_f32 v35, v174, v175
	v_cndmask_b32_e32 v32, 0, v32, vcc
	v_cndmask_b32_e32 v33, 0, v33, vcc
	v_cndmask_b32_e32 v34, 0, v34, vcc
	v_cndmask_b32_e32 v35, 0, v35, vcc
	global_load_dwordx4 v[80:83], v124, s[30:31] offset:192
	global_load_dwordx4 v[84:87], v133, s[60:61] offset:384
	global_load_dwordx4 v[88:91], v133, s[60:61] offset:400
	global_load_dwordx4 v[136:139], v125, s[34:35] offset:192
	global_load_dwordx4 v[140:143], v126, s[34:35] offset:192
	global_load_dwordx4 v[144:147], v127, s[34:35] offset:192
	global_load_dwordx4 v[148:151], v128, s[34:35] offset:192
	global_load_dwordx4 v[152:155], v129, s[34:35] offset:192
	global_load_dwordx4 v[156:159], v130, s[34:35] offset:192
	global_load_dwordx4 v[160:163], v131, s[34:35] offset:192
	global_load_dwordx4 v[164:167], v132, s[34:35] offset:192
	s_waitcnt vmcnt(18)
	v_mfma_f32_16x16x32_bf16 v[4:7], v[32:35], v[92:95], v[4:7]
	s_waitcnt vmcnt(17)
	v_mfma_f32_16x16x32_bf16 v[12:15], v[32:35], v[96:99], v[12:15]
	s_waitcnt vmcnt(16)
	v_mfma_f32_16x16x32_bf16 v[8:11], v[32:35], v[100:103], v[8:11]
	s_waitcnt vmcnt(15)
	v_mfma_f32_16x16x32_bf16 v[20:23], v[32:35], v[104:107], v[20:23]
	s_waitcnt vmcnt(14)
	v_mfma_f32_16x16x32_bf16 v[16:19], v[32:35], v[108:111], v[16:19]
	s_waitcnt vmcnt(13)
	v_mfma_f32_16x16x32_bf16 v[28:31], v[32:35], v[112:115], v[28:31]
	s_waitcnt vmcnt(12)
	v_mfma_f32_16x16x32_bf16 v[24:27], v[32:35], v[116:119], v[24:27]
	s_waitcnt vmcnt(11)
	v_mfma_f32_16x16x32_bf16 v[0:3], v[32:35], v[120:123], v[0:3]
	s_waitcnt vmcnt(8)
	v_lshlrev_b32_e32 v168, 16, v80
	v_and_b32_e32 v169, 0xffff0000, v80
	v_lshlrev_b32_e32 v170, 16, v81
	v_and_b32_e32 v171, 0xffff0000, v81
	v_lshlrev_b32_e32 v172, 16, v82
	v_and_b32_e32 v173, 0xffff0000, v82
	v_lshlrev_b32_e32 v174, 16, v83
	v_and_b32_e32 v175, 0xffff0000, v83
	v_pk_add_f32 v[168:169], v[84:85], v[168:169]
	v_pk_add_f32 v[170:171], v[86:87], v[170:171]
	v_pk_add_f32 v[172:173], v[88:89], v[172:173]
	v_pk_add_f32 v[174:175], v[90:91], v[174:175]
	v_cvt_pk_bf16_f32 v32, v168, v169
	v_cvt_pk_bf16_f32 v33, v170, v171
	v_cvt_pk_bf16_f32 v34, v172, v173
	v_cvt_pk_bf16_f32 v35, v174, v175
	v_cndmask_b32_e32 v32, 0, v32, vcc
	v_cndmask_b32_e32 v33, 0, v33, vcc
	v_cndmask_b32_e32 v34, 0, v34, vcc
	v_cndmask_b32_e32 v35, 0, v35, vcc
	s_nop 1
	s_waitcnt vmcnt(7)
	v_mfma_f32_16x16x32_bf16 v[4:7], v[32:35], v[136:139], v[4:7]
	s_waitcnt vmcnt(6)
	v_mfma_f32_16x16x32_bf16 v[12:15], v[32:35], v[140:143], v[12:15]
	s_waitcnt vmcnt(5)
	v_mfma_f32_16x16x32_bf16 v[8:11], v[32:35], v[144:147], v[8:11]
	s_waitcnt vmcnt(4)
	v_mfma_f32_16x16x32_bf16 v[20:23], v[32:35], v[148:151], v[20:23]
	s_waitcnt vmcnt(3)
	v_mfma_f32_16x16x32_bf16 v[16:19], v[32:35], v[152:155], v[16:19]
	s_waitcnt vmcnt(2)
	v_mfma_f32_16x16x32_bf16 v[28:31], v[32:35], v[156:159], v[28:31]
	s_waitcnt vmcnt(1)
	v_mfma_f32_16x16x32_bf16 v[24:27], v[32:35], v[160:163], v[24:27]
	s_waitcnt vmcnt(0)
	v_mfma_f32_16x16x32_bf16 v[0:3], v[32:35], v[164:167], v[0:3]
	s_nop 7
	s_branch .LBB0_546
